# v29gepi
# speedup vs baseline: 1.0059x; 1.0059x over previous
; __device__ __forceinline__ float bf2f(u16 b) { return __uint_as_float(((unsigned)b) << 16); }
; __device__ __forceinline__ float silu_f(float g) { return g * __builtin_amdgcn_rcpf(1.f + __builtin_amdgcn_exp2f(-g * LOG2E)); }
; template <int EPI>
; __device__ __forceinline__ void epilogue(const Params& p, int pass, int layer, int pm, int pn,
;                                          f32x4 (&acc)[2][2][4][2], const float* xin, float* xout) {
;     ...
;     int t0 = pm * 256;
;     u16* Y = (u16*)(p.ws + OFF_Y);
;     const float* stat = (const float*)(p.ws + OFF_STAT0);
;     int h = pn >> 1;
;     float gn[2][2];
; #pragma unroll
;     for (int bj = 0; bj < 2; ++bj)
; #pragma unroll
;       for (int n = 0; n < 2; ++n) gn[bj][n] = p.ret_gn[pn * 256 + bj * 128 + wc * 32 + n * 16 + fr];
; #pragma unroll
;     for (int ai = 0; ai < 2; ++ai)
; #pragma unroll
;       for (int m = 0; m < 4; ++m) {
;         int tb = t0 + ai * 128 + wr * 64 + m * 16 + fq * 4;
;         asm volatile("" : "+v"(tb));
;         float4 s01[4], s23[4];
;         u16 yv[4][2][2];
; #pragma unroll
;         for (int j = 0; j < 4; ++j) {
;           const float4* sp = (const float4*)(stat + ((long)(tb + j) * 8 + h) * 8);
;           s01[j] = sp[0]; s23[j] = sp[1];
; #pragma unroll
;           for (int bj = 0; bj < 2; ++bj)
; #pragma unroll
;             for (int n = 0; n < 2; ++n)
;               yv[j][bj][n] = Y[(long)(tb + j) * YS + pn * 256 + bj * 128 + wc * 32 + n * 16 + fr];
;         }
; #pragma unroll
;         for (int j = 0; j < 4; ++j) {
;           float s1 = s01[j].x + s01[j].z + s23[j].x + s23[j].z, s2 = s01[j].y + s01[j].w + s23[j].y + s23[j].w;
;           float mu = s1 * (1.f / 512.f);
;           float var = s2 * (1.f / 512.f) - mu * mu;
;           float rstd = rsqrtf(fmaxf(var, 0.f) + 1e-5f);
; #pragma unroll
;           for (int bj = 0; bj < 2; ++bj)
; #pragma unroll
;             for (int n = 0; n < 2; ++n) {
;               float g = acc[ai][bj][m][n][j];
;               float yn = (bf2f(yv[j][bj][n]) - mu) * rstd * gn[bj][n];
;               Y[(long)(tb + j) * YS + pn * 256 + bj * 128 + wc * 32 + n * 16 + fr] = f2bf(silu_f(g) * yn);
;             }
;         }
.LBB0_54:
	v_mbcnt_lo_u32_b32 v0, -1, 0
	v_mbcnt_hi_u32_b32 v0, -1, v0
	s_lshl_b32 s18, s3, 8
	v_or_b32_e32 v132, s33, v0
	v_lshrrev_b32_e32 v130, 1, v132
	v_and_b32_e32 v133, 15, v0
	v_and_b32_e32 v134, 0x60, v130
	s_lshl_b32 s1, s14, 8
	s_ashr_i32 s14, s3, 1
	v_or3_b32 v130, v133, s18, v134
	v_readlane_b32 s40, v252, 16
	v_lshrrev_b32_e32 v0, 2, v0
	s_ashr_i32 s15, s14, 31
	v_ashrrev_i32_e32 v131, 31, v130
	v_readlane_b32 s54, v252, 30
	v_readlane_b32 s55, v252, 31
	v_and_or_b32 v0, v0, 12, s1
	s_lshl_b64 s[14:15], s[14:15], 5
	v_readlane_b32 s1, v252, 59
	v_lshl_add_u64 v[130:131], v[130:131], 2, s[54:55]
	s_add_u32 s16, s1, s14
	v_readlane_b32 s1, v252, 60
	global_load_dword v151, v[130:131], off
	global_load_dword v150, v[130:131], off offset:64
	global_load_dword v149, v[130:131], off offset:512
	global_load_dword v148, v[130:131], off offset:576
	v_ashrrev_i32_e32 v130, 2, v132
	s_addc_u32 s17, s1, s15
	s_ashr_i32 s19, s18, 31
	v_and_b32_e32 v130, 0xffffffc0, v130
	s_lshl_b64 s[14:15], s[18:19], 1
	v_readlane_b32 s18, v252, 61
	v_add_u32_e32 v152, v0, v130
	v_readlane_b32 s19, v252, 62
	s_add_u32 s14, s18, s14
	s_addc_u32 s15, s19, s15
	v_lshlrev_b32_e32 v0, 1, v134
	v_mov_b32_e32 v134, v152
	v_lshl_add_u64 v[130:131], s[14:15], 0, v[0:1]
	v_lshlrev_b32_e32 v0, 1, v133
	v_lshl_add_u64 v[138:139], v[130:131], 0, v[0:1]
	v_ashrrev_i32_e32 v135, 31, v134
	v_lshlrev_b64 v[130:131], 8, v[134:135]
	v_lshl_add_u64 v[136:137], s[16:17], 0, v[130:131]
	global_load_dwordx4 v[154:157], v[136:137], off offset:16
	global_load_dwordx4 v[158:161], v[136:137], off
	s_mov_b32 s18, 0x3b000000
	v_mad_i64_i32 v[142:143], s[14:15], v134, s24, v[138:139]
	global_load_ushort v162, v[142:143], off
	global_load_ushort v163, v[142:143], off offset:32
	global_load_ushort v164, v[142:143], off offset:256
	global_load_ushort v165, v[142:143], off offset:288
	v_mul_f32_e32 v153, 0xbfb8aa3b, v126
	v_exp_f32_e32 v153, v153
	v_add_u32_e32 v130, 1, v134
	v_ashrrev_i32_e32 v131, 31, v130
	v_lshlrev_b64 v[132:133], 8, v[130:131]
	v_add_f32_e32 v153, 1.0, v153
	v_rcp_f32_e32 v153, v153
	v_lshl_add_u64 v[132:133], s[16:17], 0, v[132:133]
	v_mad_i64_i32 v[144:145], s[14:15], v130, s24, v[138:139]
	global_load_ushort v166, v[144:145], off
	global_load_ushort v167, v[144:145], off offset:32
	global_load_ushort v168, v[144:145], off offset:256
	global_load_ushort v169, v[144:145], off offset:288
	v_mul_f32_e32 v126, v126, v153
	v_mul_f32_e32 v153, 0xbfb8aa3b, v122
	v_exp_f32_e32 v153, v153
	v_add_u32_e32 v140, 2, v134
	v_ashrrev_i32_e32 v141, 31, v140
	v_lshlrev_b64 v[130:131], 8, v[140:141]
	v_add_f32_e32 v153, 1.0, v153
	v_rcp_f32_e32 v153, v153
	v_lshl_add_u64 v[130:131], s[16:17], 0, v[130:131]
	v_mad_i64_i32 v[146:147], s[14:15], v140, s24, v[138:139]
	global_load_ushort v170, v[146:147], off
	global_load_ushort v171, v[146:147], off offset:32
	global_load_ushort v172, v[146:147], off offset:256
	global_load_ushort v173, v[146:147], off offset:288
	v_mul_f32_e32 v122, v122, v153
	v_mul_f32_e32 v153, 0xbfb8aa3b, v118
	v_exp_f32_e32 v153, v153
	v_add_u32_e32 v140, 3, v134
	v_ashrrev_i32_e32 v141, 31, v140
	v_lshlrev_b64 v[134:135], 8, v[140:141]
	v_add_f32_e32 v153, 1.0, v153
	v_rcp_f32_e32 v153, v153
	v_lshl_add_u64 v[134:135], s[16:17], 0, v[134:135]
	v_mad_i64_i32 v[140:141], s[14:15], v140, s24, v[138:139]
	global_load_ushort v174, v[140:141], off
	global_load_ushort v175, v[140:141], off offset:32
	global_load_ushort v176, v[140:141], off offset:256
	global_load_ushort v177, v[140:141], off offset:288
	v_mul_f32_e32 v118, v118, v153
	s_mov_b32 s3, s0
	v_readlane_b32 s41, v252, 17
	v_readlane_b32 s42, v252, 18
	v_readlane_b32 s43, v252, 19
	v_readlane_b32 s44, v252, 20
	v_readlane_b32 s45, v252, 21
	v_readlane_b32 s46, v252, 22
	v_readlane_b32 s47, v252, 23
	v_readlane_b32 s48, v252, 24
	v_readlane_b32 s49, v252, 25
	v_readlane_b32 s50, v252, 26
	v_readlane_b32 s51, v252, 27
	v_readlane_b32 s52, v252, 28
	v_readlane_b32 s53, v252, 29
	s_waitcnt vmcnt(0)
	v_pk_add_f32 v[136:137], v[158:159], v[160:161]
	s_nop 0
	v_pk_add_f32 v[136:137], v[136:137], v[154:155]
	s_nop 0
	v_pk_add_f32 v[136:137], v[136:137], v[156:157]
	s_nop 0
	v_pk_mul_f32 v[136:137], v[136:137], s[18:19] op_sel_hi:[1,0]
	s_nop 0
	v_fma_f32 v0, -v136, v136, v137
	v_max_f32_e32 v0, 0, v0
	v_add_f32_e32 v0, 0x3727c5ac, v0
	v_cmp_gt_f32_e32 vcc, s25, v0
	v_mul_f32_e32 v137, 0x4b800000, v0
	s_nop 0
	v_cndmask_b32_e32 v0, v0, v137, vcc
	v_rsq_f32_e32 v0, v0
	s_nop 0
	v_mul_f32_e32 v137, 0x45800000, v0
	v_cndmask_b32_e32 v137, v0, v137, vcc
	s_waitcnt vmcnt(0)
	v_lshlrev_b32_e32 v0, 16, v162
	v_sub_f32_e32 v0, v0, v136
	v_mul_f32_e32 v0, v0, v137
	v_mul_f32_e32 v0, v151, v0
	v_mul_f32_e32 v0, v126, v0
	v_cvt_pk_bf16_f32 v0, v0, s0
	s_waitcnt vmcnt(0)
	v_lshlrev_b32_e32 v126, 16, v163
	v_sub_f32_e32 v126, v126, v136
	v_mul_f32_e32 v126, v126, v137
	v_mul_f32_e32 v126, v150, v126
	v_mul_f32_e32 v122, v122, v126
	v_cvt_pk_bf16_f32 v122, v122, s0
	s_waitcnt vmcnt(0)
	v_lshlrev_b32_e32 v126, 16, v164
	v_sub_f32_e32 v126, v126, v136
	v_mul_f32_e32 v126, v126, v137
	v_mul_f32_e32 v126, v149, v126
	v_mul_f32_e32 v118, v118, v126
	global_load_dwordx4 v[154:157], v[132:133], off offset:16
	global_load_dwordx4 v[158:161], v[132:133], off
	v_cvt_pk_bf16_f32 v118, v118, s0
	s_waitcnt vmcnt(0)
	v_lshlrev_b32_e32 v126, 16, v165
	v_sub_f32_e32 v126, v126, v136
	v_mul_f32_e32 v136, 0xbfb8aa3b, v114
	v_exp_f32_e32 v136, v136
	s_waitcnt vmcnt(0)
; __device__ __forceinline__ float bf2f(u16 b) { return __uint_as_float(((unsigned)b) << 16); }
; __device__ __forceinline__ float silu_f(float g) { return g * __builtin_amdgcn_rcpf(1.f + __builtin_amdgcn_exp2f(-g * LOG2E)); }
; template <int EPI>
; __device__ __forceinline__ void epilogue(const Params& p, int pass, int layer, int pm, int pn,
;                                          f32x4 (&acc)[2][2][4][2], const float* xin, float* xout) {
;     ...
;       for (int m = 0; m < 4; ++m) {
;         int tb = t0 + ai * 128 + wr * 64 + m * 16 + fq * 4;
;         asm volatile("" : "+v"(tb));
;         float4 s01[4], s23[4];
;         u16 yv[4][2][2];
; #pragma unroll
;         for (int j = 0; j < 4; ++j) {
;           const float4* sp = (const float4*)(stat + ((long)(tb + j) * 8 + h) * 8);
;           s01[j] = sp[0]; s23[j] = sp[1];
; #pragma unroll
;           for (int bj = 0; bj < 2; ++bj)
; #pragma unroll
;             for (int n = 0; n < 2; ++n)
;               yv[j][bj][n] = Y[(long)(tb + j) * YS + pn * 256 + bj * 128 + wc * 32 + n * 16 + fr];
;         }
; #pragma unroll
;         for (int j = 0; j < 4; ++j) {
;           float s1 = s01[j].x + s01[j].z + s23[j].x + s23[j].z, s2 = s01[j].y + s01[j].w + s23[j].y + s23[j].w;
;           float mu = s1 * (1.f / 512.f);
;           float var = s2 * (1.f / 512.f) - mu * mu;
;           float rstd = rsqrtf(fmaxf(var, 0.f) + 1e-5f);
; #pragma unroll
;           for (int bj = 0; bj < 2; ++bj)
; #pragma unroll
;             for (int n = 0; n < 2; ++n) {
;               float g = acc[ai][bj][m][n][j];
;               float yn = (bf2f(yv[j][bj][n]) - mu) * rstd * gn[bj][n];
;               Y[(long)(tb + j) * YS + pn * 256 + bj * 128 + wc * 32 + n * 16 + fr] = f2bf(silu_f(g) * yn);
;             }
;         }
	v_pk_add_f32 v[132:133], v[158:159], v[160:161]
	v_mul_f32_e32 v126, v126, v137
	v_pk_add_f32 v[132:133], v[132:133], v[154:155]
	v_add_f32_e32 v136, 1.0, v136
	v_rcp_f32_e32 v136, v136
	v_mul_f32_e32 v126, v148, v126
	v_pk_add_f32 v[132:133], v[132:133], v[156:157]
	v_mul_f32_e32 v114, v114, v136
	v_mul_f32_e32 v114, v114, v126
	v_pk_mul_f32 v[132:133], v[132:133], s[18:19] op_sel_hi:[1,0]
	v_cvt_pk_bf16_f32 v126, v114, s0
	v_fma_f32 v114, -v132, v132, v133
	v_max_f32_e32 v114, 0, v114
	v_add_f32_e32 v114, 0x3727c5ac, v114
	v_cmp_gt_f32_e32 vcc, s25, v114
	v_mul_f32_e32 v133, 0x4b800000, v114
	v_mul_f32_e32 v136, 0xbfb8aa3b, v127
	v_cndmask_b32_e32 v114, v114, v133, vcc
	v_rsq_f32_e32 v114, v114
	v_exp_f32_e32 v136, v136
	v_mul_f32_e32 v133, 0x45800000, v114
	v_cndmask_b32_e32 v114, v114, v133, vcc
	v_add_f32_e32 v136, 1.0, v136
	v_rcp_f32_e32 v136, v136
	s_waitcnt vmcnt(0)
	v_lshlrev_b32_e32 v133, 16, v166
	v_sub_f32_e32 v133, v133, v132
	v_mul_f32_e32 v133, v133, v114
	v_mul_f32_e32 v133, v151, v133
	v_mul_f32_e32 v127, v127, v136
	v_mul_f32_e32 v127, v127, v133
	v_mul_f32_e32 v136, 0xbfb8aa3b, v123
	v_exp_f32_e32 v136, v136
	v_cvt_pk_bf16_f32 v127, v127, s0
	v_add_f32_e32 v136, 1.0, v136
	v_rcp_f32_e32 v136, v136
	s_waitcnt vmcnt(0)
	v_lshlrev_b32_e32 v133, 16, v167
	v_sub_f32_e32 v133, v133, v132
	v_mul_f32_e32 v133, v133, v114
	v_mul_f32_e32 v133, v150, v133
	v_mul_f32_e32 v123, v123, v136
	v_mul_f32_e32 v123, v123, v133
	v_mul_f32_e32 v136, 0xbfb8aa3b, v119
	v_exp_f32_e32 v136, v136
	v_cvt_pk_bf16_f32 v123, v123, s0
	v_add_f32_e32 v136, 1.0, v136
	v_rcp_f32_e32 v136, v136
	s_waitcnt vmcnt(0)
	v_lshlrev_b32_e32 v133, 16, v168
	v_sub_f32_e32 v133, v133, v132
	v_mul_f32_e32 v133, v133, v114
	v_mul_f32_e32 v133, v149, v133
	v_mul_f32_e32 v119, v119, v136
	v_mul_f32_e32 v119, v119, v133
	v_cvt_pk_bf16_f32 v119, v119, s0
	s_waitcnt vmcnt(0)
	v_lshlrev_b32_e32 v133, 16, v169
	v_sub_f32_e32 v132, v133, v132
	v_mul_f32_e32 v114, v132, v114
	v_mul_f32_e32 v132, 0xbfb8aa3b, v115
	v_exp_f32_e32 v132, v132
	v_mul_f32_e32 v114, v148, v114
	v_add_f32_e32 v132, 1.0, v132
	v_rcp_f32_e32 v132, v132
	s_nop 0
	v_mul_f32_e32 v115, v115, v132
	global_load_dwordx4 v[154:157], v[130:131], off offset:16
	s_nop 0
	global_load_dwordx4 v[130:133], v[130:131], off
	v_mul_f32_e32 v114, v115, v114
	v_cvt_pk_bf16_f32 v153, v114, s0
	s_waitcnt vmcnt(0)
	v_pk_add_f32 v[114:115], v[130:131], v[132:133]
	s_nop 0
	v_pk_add_f32 v[114:115], v[114:115], v[154:155]
	v_mul_f32_e32 v131, 0xbfb8aa3b, v128
	v_pk_add_f32 v[114:115], v[114:115], v[156:157]
	v_exp_f32_e32 v131, v131
	v_pk_mul_f32 v[114:115], v[114:115], s[18:19] op_sel_hi:[1,0]
	v_add_f32_e32 v131, 1.0, v131
	v_fma_f32 v115, -v114, v114, v115
	v_max_f32_e32 v115, 0, v115
	v_add_f32_e32 v115, 0x3727c5ac, v115
	v_cmp_gt_f32_e32 vcc, s25, v115
	v_mul_f32_e32 v130, 0x4b800000, v115
	v_rcp_f32_e32 v131, v131
	v_cndmask_b32_e32 v115, v115, v130, vcc
	v_rsq_f32_e32 v115, v115
	v_mul_f32_e32 v128, v128, v131
	v_mul_f32_e32 v131, 0xbfb8aa3b, v124
	v_mul_f32_e32 v130, 0x45800000, v115
	v_cndmask_b32_e32 v130, v115, v130, vcc
	v_exp_f32_e32 v131, v131
	s_waitcnt vmcnt(0)
	v_lshlrev_b32_e32 v115, 16, v170
	v_sub_f32_e32 v115, v115, v114
	v_mul_f32_e32 v115, v115, v130
	v_mul_f32_e32 v115, v151, v115
	v_mul_f32_e32 v115, v128, v115
	v_add_f32_e32 v131, 1.0, v131
	v_rcp_f32_e32 v131, v131
	v_cvt_pk_bf16_f32 v115, v115, s0
	v_mul_f32_e32 v124, v124, v131
	v_mul_f32_e32 v131, 0xbfb8aa3b, v120
	v_exp_f32_e32 v131, v131
	s_waitcnt vmcnt(0)
	v_lshlrev_b32_e32 v128, 16, v171
	v_sub_f32_e32 v128, v128, v114
	v_mul_f32_e32 v128, v128, v130
	v_mul_f32_e32 v128, v150, v128
	v_mul_f32_e32 v124, v124, v128
	v_add_f32_e32 v131, 1.0, v131
	v_rcp_f32_e32 v131, v131
	v_cvt_pk_bf16_f32 v124, v124, s0
	v_mul_f32_e32 v120, v120, v131
	s_waitcnt vmcnt(0)
	v_lshlrev_b32_e32 v128, 16, v172
	v_sub_f32_e32 v128, v128, v114
	v_mul_f32_e32 v128, v128, v130
	v_mul_f32_e32 v128, v149, v128
	v_mul_f32_e32 v120, v120, v128
	v_cvt_pk_bf16_f32 v120, v120, s0
	s_waitcnt vmcnt(0)
	v_lshlrev_b32_e32 v128, 16, v173
	v_sub_f32_e32 v114, v128, v114
	v_mul_f32_e32 v128, 0xbfb8aa3b, v116
	v_exp_f32_e32 v128, v128
	v_mul_f32_e32 v114, v114, v130
	v_mul_f32_e32 v114, v148, v114
	v_add_f32_e32 v128, 1.0, v128
	v_rcp_f32_e32 v128, v128
	s_nop 0
	v_mul_f32_e32 v116, v116, v128
	v_mul_f32_e32 v114, v116, v114
	global_load_dwordx4 v[130:133], v[134:135], off offset:16
	s_nop 0
	global_load_dwordx4 v[134:137], v[134:135], off
	s_nop 0
	v_cvt_pk_bf16_f32 v114, v114, s0
	global_store_short v[142:143], v0, off
	global_store_short v[142:143], v122, off offset:32
	global_store_short v[142:143], v118, off offset:256
	global_store_short v[142:143], v126, off offset:288
	global_store_short v[144:145], v127, off
	global_store_short v[144:145], v123, off offset:32
	global_store_short v[144:145], v119, off offset:256
	global_store_short v[144:145], v153, off offset:288
	global_store_short v[146:147], v115, off
	global_store_short v[146:147], v124, off offset:32
	global_store_short v[146:147], v120, off offset:256
	global_store_short v[146:147], v114, off offset:288
	v_or_b32_e32 v118, 16, v152
	s_waitcnt vmcnt(0)
	v_pk_add_f32 v[114:115], v[134:135], v[136:137]
	s_nop 0
	v_pk_add_f32 v[114:115], v[114:115], v[130:131]
	s_nop 0
	v_pk_add_f32 v[114:115], v[114:115], v[132:133]
	s_nop 0
	v_pk_mul_f32 v[114:115], v[114:115], s[18:19] op_sel_hi:[1,0]
	s_nop 0
	v_fma_f32 v0, -v114, v114, v115
	v_max_f32_e32 v0, 0, v0
	v_add_f32_e32 v0, 0x3727c5ac, v0
	v_cmp_gt_f32_e32 vcc, s25, v0
	v_mul_f32_e32 v115, 0x4b800000, v0
	s_nop 0
	v_cndmask_b32_e32 v0, v0, v115, vcc
	v_rsq_f32_e32 v0, v0
	s_nop 0
	v_mul_f32_e32 v115, 0x45800000, v0
	v_cndmask_b32_e32 v0, v0, v115, vcc
	s_waitcnt vmcnt(0)
; __device__ __forceinline__ float bf2f(u16 b) { return __uint_as_float(((unsigned)b) << 16); }
; __device__ __forceinline__ float silu_f(float g) { return g * __builtin_amdgcn_rcpf(1.f + __builtin_amdgcn_exp2f(-g * LOG2E)); }
; template <int EPI>
; __device__ __forceinline__ void epilogue(const Params& p, int pass, int layer, int pm, int pn,
;                                          f32x4 (&acc)[2][2][4][2], const float* xin, float* xout) {
;     ...
;       for (int m = 0; m < 4; ++m) {
;         int tb = t0 + ai * 128 + wr * 64 + m * 16 + fq * 4;
;         asm volatile("" : "+v"(tb));
;         float4 s01[4], s23[4];
;         u16 yv[4][2][2];
; #pragma unroll
;         for (int j = 0; j < 4; ++j) {
;           const float4* sp = (const float4*)(stat + ((long)(tb + j) * 8 + h) * 8);
;           s01[j] = sp[0]; s23[j] = sp[1];
; #pragma unroll
;           for (int bj = 0; bj < 2; ++bj)
; #pragma unroll
;             for (int n = 0; n < 2; ++n)
;               yv[j][bj][n] = Y[(long)(tb + j) * YS + pn * 256 + bj * 128 + wc * 32 + n * 16 + fr];
;         }
; #pragma unroll
;         for (int j = 0; j < 4; ++j) {
;           float s1 = s01[j].x + s01[j].z + s23[j].x + s23[j].z, s2 = s01[j].y + s01[j].w + s23[j].y + s23[j].w;
;           float mu = s1 * (1.f / 512.f);
;           float var = s2 * (1.f / 512.f) - mu * mu;
;           float rstd = rsqrtf(fmaxf(var, 0.f) + 1e-5f);
; #pragma unroll
;           for (int bj = 0; bj < 2; ++bj)
; #pragma unroll
;             for (int n = 0; n < 2; ++n) {
;               float g = acc[ai][bj][m][n][j];
;               float yn = (bf2f(yv[j][bj][n]) - mu) * rstd * gn[bj][n];
;               Y[(long)(tb + j) * YS + pn * 256 + bj * 128 + wc * 32 + n * 16 + fr] = f2bf(silu_f(g) * yn);
;             }
;         }
	v_lshlrev_b32_e32 v115, 16, v174
	v_mul_f32_e32 v116, 0xbfb8aa3b, v129
	v_exp_f32_e32 v116, v116
	v_sub_f32_e32 v115, v115, v114
	v_mul_f32_e32 v115, v115, v0
	v_mul_f32_e32 v115, v151, v115
	v_add_f32_e32 v116, 1.0, v116
	v_rcp_f32_e32 v116, v116
	s_nop 0
	v_mul_f32_e32 v116, v129, v116
	v_mul_f32_e32 v115, v116, v115
	v_mul_f32_e32 v116, 0xbfb8aa3b, v125
	v_exp_f32_e32 v116, v116
	v_cvt_pk_bf16_f32 v115, v115, s0
	global_store_short v[140:141], v115, off
	s_waitcnt vmcnt(0)
	v_lshlrev_b32_e32 v115, 16, v175
	v_add_f32_e32 v116, 1.0, v116
	v_rcp_f32_e32 v116, v116
	v_sub_f32_e32 v115, v115, v114
	v_mul_f32_e32 v115, v115, v0
	v_mul_f32_e32 v115, v150, v115
	v_mul_f32_e32 v116, v125, v116
	v_mul_f32_e32 v115, v116, v115
	v_mul_f32_e32 v116, 0xbfb8aa3b, v121
	v_exp_f32_e32 v116, v116
	v_cvt_pk_bf16_f32 v115, v115, s0
	global_store_short v[140:141], v115, off offset:32
	s_waitcnt vmcnt(0)
	v_lshlrev_b32_e32 v115, 16, v176
	v_add_f32_e32 v116, 1.0, v116
	v_rcp_f32_e32 v116, v116
	v_sub_f32_e32 v115, v115, v114
	v_mul_f32_e32 v115, v115, v0
	v_mul_f32_e32 v115, v149, v115
	v_mul_f32_e32 v116, v121, v116
	v_mul_f32_e32 v115, v116, v115
	v_cvt_pk_bf16_f32 v115, v115, s0
	global_store_short v[140:141], v115, off offset:256
	s_waitcnt vmcnt(0)
	v_lshlrev_b32_e32 v115, 16, v177
	v_sub_f32_e32 v114, v115, v114
	v_mul_f32_e32 v0, v114, v0
	v_mul_f32_e32 v114, 0xbfb8aa3b, v117
	v_exp_f32_e32 v114, v114
	v_mul_f32_e32 v0, v148, v0
	v_add_f32_e32 v114, 1.0, v114
	v_rcp_f32_e32 v114, v114
	s_nop 0
	v_mul_f32_e32 v114, v117, v114
	v_mul_f32_e32 v0, v114, v0
	v_cvt_pk_bf16_f32 v0, v0, s0
	global_store_short v[140:141], v0, off offset:288
	s_nop 0
	v_ashrrev_i32_e32 v119, 31, v118
	v_lshlrev_b64 v[114:115], 8, v[118:119]
	v_lshl_add_u64 v[120:121], s[16:17], 0, v[114:115]
	global_load_dwordx4 v[130:133], v[120:121], off offset:16
	global_load_dwordx4 v[134:137], v[120:121], off
	v_mad_i64_i32 v[124:125], s[14:15], v118, s24, v[138:139]
	global_load_ushort v178, v[124:125], off
	global_load_ushort v179, v[124:125], off offset:32
	global_load_ushort v180, v[124:125], off offset:256
	global_load_ushort v181, v[124:125], off offset:288
	v_add_u32_e32 v114, 1, v118
	v_ashrrev_i32_e32 v115, 31, v114
	v_lshlrev_b64 v[116:117], 8, v[114:115]
	v_lshl_add_u64 v[116:117], s[16:17], 0, v[116:117]
	v_mad_i64_i32 v[126:127], s[14:15], v114, s24, v[138:139]
	global_load_ushort v182, v[126:127], off
	global_load_ushort v183, v[126:127], off offset:32
	global_load_ushort v184, v[126:127], off offset:256
	global_load_ushort v185, v[126:127], off offset:288
	v_add_u32_e32 v122, 2, v118
	v_ashrrev_i32_e32 v123, 31, v122
	v_lshlrev_b64 v[114:115], 8, v[122:123]
	v_lshl_add_u64 v[114:115], s[16:17], 0, v[114:115]
	v_mad_i64_i32 v[128:129], s[14:15], v122, s24, v[138:139]
	global_load_ushort v186, v[128:129], off
	global_load_ushort v187, v[128:129], off offset:32
	global_load_ushort v188, v[128:129], off offset:256
	global_load_ushort v189, v[128:129], off offset:288
	v_add_u32_e32 v122, 3, v118
	v_ashrrev_i32_e32 v123, 31, v122
	v_lshlrev_b64 v[118:119], 8, v[122:123]
	v_lshl_add_u64 v[118:119], s[16:17], 0, v[118:119]
	v_mad_i64_i32 v[122:123], s[14:15], v122, s24, v[138:139]
	global_load_ushort v190, v[122:123], off
	global_load_ushort v191, v[122:123], off offset:32
	global_load_ushort v192, v[122:123], off offset:256
	global_load_ushort v193, v[122:123], off offset:288
	s_waitcnt vmcnt(0)
	v_pk_add_f32 v[120:121], v[134:135], v[136:137]
	s_nop 0
	v_pk_add_f32 v[120:121], v[120:121], v[130:131]
	v_mul_f32_e32 v130, 0xbfb8aa3b, v110
	v_pk_add_f32 v[120:121], v[120:121], v[132:133]
	v_exp_f32_e32 v130, v130
	v_pk_mul_f32 v[120:121], v[120:121], s[18:19] op_sel_hi:[1,0]
	v_add_f32_e32 v130, 1.0, v130
	v_fma_f32 v0, -v120, v120, v121
	v_max_f32_e32 v0, 0, v0
	v_add_f32_e32 v0, 0x3727c5ac, v0
	v_cmp_gt_f32_e32 vcc, s25, v0
	v_mul_f32_e32 v121, 0x4b800000, v0
	v_rcp_f32_e32 v130, v130
	v_cndmask_b32_e32 v0, v0, v121, vcc
	v_rsq_f32_e32 v0, v0
	v_mul_f32_e32 v110, v110, v130
	v_mul_f32_e32 v130, 0xbfb8aa3b, v106
	v_mul_f32_e32 v121, 0x45800000, v0
	v_cndmask_b32_e32 v121, v0, v121, vcc
	v_exp_f32_e32 v130, v130
	s_waitcnt vmcnt(0)
	v_lshlrev_b32_e32 v0, 16, v178
	v_sub_f32_e32 v0, v0, v120
	v_mul_f32_e32 v0, v0, v121
	v_mul_f32_e32 v0, v151, v0
	v_mul_f32_e32 v0, v110, v0
	v_add_f32_e32 v130, 1.0, v130
	v_rcp_f32_e32 v130, v130
	v_cvt_pk_bf16_f32 v0, v0, s0
	v_mul_f32_e32 v106, v106, v130
	v_mul_f32_e32 v130, 0xbfb8aa3b, v102
	v_exp_f32_e32 v130, v130
	s_waitcnt vmcnt(0)
	v_lshlrev_b32_e32 v110, 16, v179
	v_sub_f32_e32 v110, v110, v120
	v_mul_f32_e32 v110, v110, v121
	v_mul_f32_e32 v110, v150, v110
	v_mul_f32_e32 v106, v106, v110
	v_add_f32_e32 v130, 1.0, v130
	v_rcp_f32_e32 v130, v130
	v_cvt_pk_bf16_f32 v106, v106, s0
	v_mul_f32_e32 v102, v102, v130
	s_waitcnt vmcnt(0)
	v_lshlrev_b32_e32 v110, 16, v180
	v_sub_f32_e32 v110, v110, v120
	v_mul_f32_e32 v110, v110, v121
	v_mul_f32_e32 v110, v149, v110
	v_mul_f32_e32 v102, v102, v110
	global_load_dwordx4 v[130:133], v[116:117], off offset:16
	global_load_dwordx4 v[134:137], v[116:117], off
	v_cvt_pk_bf16_f32 v102, v102, s0
	s_waitcnt vmcnt(0)
	v_lshlrev_b32_e32 v110, 16, v181
	v_sub_f32_e32 v110, v110, v120
	v_mul_f32_e32 v120, 0xbfb8aa3b, v98
	v_exp_f32_e32 v120, v120
	s_waitcnt vmcnt(0)
; __device__ __forceinline__ float bf2f(u16 b) { return __uint_as_float(((unsigned)b) << 16); }
; __device__ __forceinline__ float silu_f(float g) { return g * __builtin_amdgcn_rcpf(1.f + __builtin_amdgcn_exp2f(-g * LOG2E)); }
; template <int EPI>
; __device__ __forceinline__ void epilogue(const Params& p, int pass, int layer, int pm, int pn,
;                                          f32x4 (&acc)[2][2][4][2], const float* xin, float* xout) {
;     ...
;       for (int m = 0; m < 4; ++m) {
;         int tb = t0 + ai * 128 + wr * 64 + m * 16 + fq * 4;
;         asm volatile("" : "+v"(tb));
;         float4 s01[4], s23[4];
;         u16 yv[4][2][2];
; #pragma unroll
;         for (int j = 0; j < 4; ++j) {
;           const float4* sp = (const float4*)(stat + ((long)(tb + j) * 8 + h) * 8);
;           s01[j] = sp[0]; s23[j] = sp[1];
; #pragma unroll
;           for (int bj = 0; bj < 2; ++bj)
; #pragma unroll
;             for (int n = 0; n < 2; ++n)
;               yv[j][bj][n] = Y[(long)(tb + j) * YS + pn * 256 + bj * 128 + wc * 32 + n * 16 + fr];
;         }
; #pragma unroll
;         for (int j = 0; j < 4; ++j) {
;           float s1 = s01[j].x + s01[j].z + s23[j].x + s23[j].z, s2 = s01[j].y + s01[j].w + s23[j].y + s23[j].w;
;           float mu = s1 * (1.f / 512.f);
;           float var = s2 * (1.f / 512.f) - mu * mu;
;           float rstd = rsqrtf(fmaxf(var, 0.f) + 1e-5f);
; #pragma unroll
;           for (int bj = 0; bj < 2; ++bj)
; #pragma unroll
;             for (int n = 0; n < 2; ++n) {
;               float g = acc[ai][bj][m][n][j];
;               float yn = (bf2f(yv[j][bj][n]) - mu) * rstd * gn[bj][n];
;               Y[(long)(tb + j) * YS + pn * 256 + bj * 128 + wc * 32 + n * 16 + fr] = f2bf(silu_f(g) * yn);
;             }
;         }
	v_pk_add_f32 v[116:117], v[134:135], v[136:137]
	v_mul_f32_e32 v110, v110, v121
	v_pk_add_f32 v[116:117], v[116:117], v[130:131]
	v_add_f32_e32 v120, 1.0, v120
	v_rcp_f32_e32 v120, v120
	v_mul_f32_e32 v110, v148, v110
	v_pk_add_f32 v[116:117], v[116:117], v[132:133]
	v_mul_f32_e32 v98, v98, v120
	v_mul_f32_e32 v98, v98, v110
	v_pk_mul_f32 v[116:117], v[116:117], s[18:19] op_sel_hi:[1,0]
	v_cvt_pk_bf16_f32 v110, v98, s0
	v_fma_f32 v98, -v116, v116, v117
	v_max_f32_e32 v98, 0, v98
	v_add_f32_e32 v98, 0x3727c5ac, v98
	v_cmp_gt_f32_e32 vcc, s25, v98
	v_mul_f32_e32 v117, 0x4b800000, v98
	v_mul_f32_e32 v120, 0xbfb8aa3b, v111
	v_cndmask_b32_e32 v98, v98, v117, vcc
	v_rsq_f32_e32 v98, v98
	v_exp_f32_e32 v120, v120
	v_mul_f32_e32 v117, 0x45800000, v98
	v_cndmask_b32_e32 v98, v98, v117, vcc
	v_add_f32_e32 v120, 1.0, v120
	v_rcp_f32_e32 v120, v120
	s_waitcnt vmcnt(0)
	v_lshlrev_b32_e32 v117, 16, v182
	v_sub_f32_e32 v117, v117, v116
	v_mul_f32_e32 v117, v117, v98
	v_mul_f32_e32 v117, v151, v117
	v_mul_f32_e32 v111, v111, v120
	v_mul_f32_e32 v111, v111, v117
	v_mul_f32_e32 v120, 0xbfb8aa3b, v107
	v_exp_f32_e32 v120, v120
	v_cvt_pk_bf16_f32 v111, v111, s0
	v_add_f32_e32 v120, 1.0, v120
	v_rcp_f32_e32 v120, v120
	s_waitcnt vmcnt(0)
	v_lshlrev_b32_e32 v117, 16, v183
	v_sub_f32_e32 v117, v117, v116
	v_mul_f32_e32 v117, v117, v98
	v_mul_f32_e32 v117, v150, v117
	v_mul_f32_e32 v107, v107, v120
	v_mul_f32_e32 v107, v107, v117
	v_mul_f32_e32 v120, 0xbfb8aa3b, v103
	v_exp_f32_e32 v120, v120
	v_cvt_pk_bf16_f32 v107, v107, s0
	v_add_f32_e32 v120, 1.0, v120
	v_rcp_f32_e32 v120, v120
	s_waitcnt vmcnt(0)
	v_lshlrev_b32_e32 v117, 16, v184
	v_sub_f32_e32 v117, v117, v116
	v_mul_f32_e32 v117, v117, v98
	v_mul_f32_e32 v117, v149, v117
	v_mul_f32_e32 v103, v103, v120
	v_mul_f32_e32 v103, v103, v117
	v_cvt_pk_bf16_f32 v103, v103, s0
	s_waitcnt vmcnt(0)
	v_lshlrev_b32_e32 v117, 16, v185
	v_sub_f32_e32 v116, v117, v116
	v_mul_f32_e32 v98, v116, v98
	v_mul_f32_e32 v116, 0xbfb8aa3b, v99
	v_exp_f32_e32 v116, v116
	v_mul_f32_e32 v98, v148, v98
	v_add_f32_e32 v116, 1.0, v116
	v_rcp_f32_e32 v116, v116
	s_nop 0
	v_mul_f32_e32 v99, v99, v116
	global_load_dwordx4 v[132:135], v[114:115], off offset:16
	s_nop 0
	global_load_dwordx4 v[114:117], v[114:115], off
	v_mul_f32_e32 v98, v99, v98
	v_cvt_pk_bf16_f32 v130, v98, s0
	s_waitcnt vmcnt(0)
	v_pk_add_f32 v[98:99], v[114:115], v[116:117]
	s_nop 0
	v_pk_add_f32 v[98:99], v[98:99], v[132:133]
	v_mul_f32_e32 v115, 0xbfb8aa3b, v112
	v_pk_add_f32 v[98:99], v[98:99], v[134:135]
	v_exp_f32_e32 v115, v115
	v_pk_mul_f32 v[98:99], v[98:99], s[18:19] op_sel_hi:[1,0]
	v_add_f32_e32 v115, 1.0, v115
	v_fma_f32 v99, -v98, v98, v99
	v_max_f32_e32 v99, 0, v99
	v_add_f32_e32 v99, 0x3727c5ac, v99
	v_cmp_gt_f32_e32 vcc, s25, v99
	v_mul_f32_e32 v114, 0x4b800000, v99
	v_rcp_f32_e32 v115, v115
	v_cndmask_b32_e32 v99, v99, v114, vcc
	v_rsq_f32_e32 v99, v99
	v_mul_f32_e32 v112, v112, v115
	v_mul_f32_e32 v115, 0xbfb8aa3b, v108
	v_mul_f32_e32 v114, 0x45800000, v99
	v_cndmask_b32_e32 v114, v99, v114, vcc
	v_exp_f32_e32 v115, v115
	s_waitcnt vmcnt(0)
	v_lshlrev_b32_e32 v99, 16, v186
	v_sub_f32_e32 v99, v99, v98
	v_mul_f32_e32 v99, v99, v114
	v_mul_f32_e32 v99, v151, v99
	v_mul_f32_e32 v99, v112, v99
	v_add_f32_e32 v115, 1.0, v115
	v_rcp_f32_e32 v115, v115
	v_cvt_pk_bf16_f32 v99, v99, s0
	v_mul_f32_e32 v108, v108, v115
	v_mul_f32_e32 v115, 0xbfb8aa3b, v104
	v_exp_f32_e32 v115, v115
	s_waitcnt vmcnt(0)
	v_lshlrev_b32_e32 v112, 16, v187
	v_sub_f32_e32 v112, v112, v98
	v_mul_f32_e32 v112, v112, v114
	v_mul_f32_e32 v112, v150, v112
	v_mul_f32_e32 v108, v108, v112
	v_add_f32_e32 v115, 1.0, v115
	v_rcp_f32_e32 v115, v115
	v_cvt_pk_bf16_f32 v108, v108, s0
	v_mul_f32_e32 v104, v104, v115
	s_waitcnt vmcnt(0)
	v_lshlrev_b32_e32 v112, 16, v188
	v_sub_f32_e32 v112, v112, v98
	v_mul_f32_e32 v112, v112, v114
	v_mul_f32_e32 v112, v149, v112
	v_mul_f32_e32 v104, v104, v112
	v_cvt_pk_bf16_f32 v104, v104, s0
	s_waitcnt vmcnt(0)
	v_lshlrev_b32_e32 v112, 16, v189
	v_sub_f32_e32 v98, v112, v98
	v_mul_f32_e32 v112, 0xbfb8aa3b, v100
	v_exp_f32_e32 v112, v112
	v_mul_f32_e32 v98, v98, v114
	v_mul_f32_e32 v98, v148, v98
	v_add_f32_e32 v112, 1.0, v112
	v_rcp_f32_e32 v112, v112
	s_nop 0
	v_mul_f32_e32 v100, v100, v112
	v_mul_f32_e32 v98, v100, v98
	global_load_dwordx4 v[114:117], v[118:119], off offset:16
	s_nop 0
	global_load_dwordx4 v[118:121], v[118:119], off
	s_nop 0
	v_cvt_pk_bf16_f32 v98, v98, s0
	global_store_short v[124:125], v0, off
	global_store_short v[124:125], v106, off offset:32
	global_store_short v[124:125], v102, off offset:256
	global_store_short v[124:125], v110, off offset:288
	global_store_short v[126:127], v111, off
	global_store_short v[126:127], v107, off offset:32
	global_store_short v[126:127], v103, off offset:256
	global_store_short v[126:127], v130, off offset:288
	global_store_short v[128:129], v99, off
	global_store_short v[128:129], v108, off offset:32
	global_store_short v[128:129], v104, off offset:256
	global_store_short v[128:129], v98, off offset:288
	v_or_b32_e32 v102, 32, v152
	s_waitcnt vmcnt(0)
	v_pk_add_f32 v[98:99], v[118:119], v[120:121]
	s_nop 0
	v_pk_add_f32 v[98:99], v[98:99], v[114:115]
	s_nop 0
	v_pk_add_f32 v[98:99], v[98:99], v[116:117]
	s_nop 0
	v_pk_mul_f32 v[98:99], v[98:99], s[18:19] op_sel_hi:[1,0]
	s_nop 0
	v_fma_f32 v0, -v98, v98, v99
	v_max_f32_e32 v0, 0, v0
	v_add_f32_e32 v0, 0x3727c5ac, v0
	v_cmp_gt_f32_e32 vcc, s25, v0
	v_mul_f32_e32 v99, 0x4b800000, v0
	s_nop 0
	v_cndmask_b32_e32 v0, v0, v99, vcc
	v_rsq_f32_e32 v0, v0
	s_nop 0
	v_mul_f32_e32 v99, 0x45800000, v0
	v_cndmask_b32_e32 v0, v0, v99, vcc
	s_waitcnt vmcnt(0)
; __device__ __forceinline__ float bf2f(u16 b) { return __uint_as_float(((unsigned)b) << 16); }
; __device__ __forceinline__ float silu_f(float g) { return g * __builtin_amdgcn_rcpf(1.f + __builtin_amdgcn_exp2f(-g * LOG2E)); }
; template <int EPI>
; __device__ __forceinline__ void epilogue(const Params& p, int pass, int layer, int pm, int pn,
;                                          f32x4 (&acc)[2][2][4][2], const float* xin, float* xout) {
;     ...
;       for (int m = 0; m < 4; ++m) {
;         int tb = t0 + ai * 128 + wr * 64 + m * 16 + fq * 4;
;         asm volatile("" : "+v"(tb));
;         float4 s01[4], s23[4];
;         u16 yv[4][2][2];
; #pragma unroll
;         for (int j = 0; j < 4; ++j) {
;           const float4* sp = (const float4*)(stat + ((long)(tb + j) * 8 + h) * 8);
;           s01[j] = sp[0]; s23[j] = sp[1];
; #pragma unroll
;           for (int bj = 0; bj < 2; ++bj)
; #pragma unroll
;             for (int n = 0; n < 2; ++n)
;               yv[j][bj][n] = Y[(long)(tb + j) * YS + pn * 256 + bj * 128 + wc * 32 + n * 16 + fr];
;         }
; #pragma unroll
;         for (int j = 0; j < 4; ++j) {
;           float s1 = s01[j].x + s01[j].z + s23[j].x + s23[j].z, s2 = s01[j].y + s01[j].w + s23[j].y + s23[j].w;
;           float mu = s1 * (1.f / 512.f);
;           float var = s2 * (1.f / 512.f) - mu * mu;
;           float rstd = rsqrtf(fmaxf(var, 0.f) + 1e-5f);
; #pragma unroll
;           for (int bj = 0; bj < 2; ++bj)
; #pragma unroll
;             for (int n = 0; n < 2; ++n) {
;               float g = acc[ai][bj][m][n][j];
;               float yn = (bf2f(yv[j][bj][n]) - mu) * rstd * gn[bj][n];
;               Y[(long)(tb + j) * YS + pn * 256 + bj * 128 + wc * 32 + n * 16 + fr] = f2bf(silu_f(g) * yn);
;             }
;         }
	v_lshlrev_b32_e32 v99, 16, v190
	v_mul_f32_e32 v100, 0xbfb8aa3b, v113
	v_exp_f32_e32 v100, v100
	v_sub_f32_e32 v99, v99, v98
	v_mul_f32_e32 v99, v99, v0
	v_mul_f32_e32 v99, v151, v99
	v_add_f32_e32 v100, 1.0, v100
	v_rcp_f32_e32 v100, v100
	s_nop 0
	v_mul_f32_e32 v100, v113, v100
	v_mul_f32_e32 v99, v100, v99
	v_mul_f32_e32 v100, 0xbfb8aa3b, v109
	v_exp_f32_e32 v100, v100
	v_cvt_pk_bf16_f32 v99, v99, s0
	global_store_short v[122:123], v99, off
	s_waitcnt vmcnt(0)
	v_lshlrev_b32_e32 v99, 16, v191
	v_add_f32_e32 v100, 1.0, v100
	v_rcp_f32_e32 v100, v100
	v_sub_f32_e32 v99, v99, v98
	v_mul_f32_e32 v99, v99, v0
	v_mul_f32_e32 v99, v150, v99
	v_mul_f32_e32 v100, v109, v100
	v_mul_f32_e32 v99, v100, v99
	v_mul_f32_e32 v100, 0xbfb8aa3b, v105
	v_exp_f32_e32 v100, v100
	v_cvt_pk_bf16_f32 v99, v99, s0
	global_store_short v[122:123], v99, off offset:32
	s_waitcnt vmcnt(0)
	v_lshlrev_b32_e32 v99, 16, v192
	v_add_f32_e32 v100, 1.0, v100
	v_rcp_f32_e32 v100, v100
	v_sub_f32_e32 v99, v99, v98
	v_mul_f32_e32 v99, v99, v0
	v_mul_f32_e32 v99, v149, v99
	v_mul_f32_e32 v100, v105, v100
	v_mul_f32_e32 v99, v100, v99
	v_cvt_pk_bf16_f32 v99, v99, s0
	global_store_short v[122:123], v99, off offset:256
	s_waitcnt vmcnt(0)
	v_lshlrev_b32_e32 v99, 16, v193
	v_sub_f32_e32 v98, v99, v98
	v_mul_f32_e32 v0, v98, v0
	v_mul_f32_e32 v98, 0xbfb8aa3b, v101
	v_exp_f32_e32 v98, v98
	v_mul_f32_e32 v0, v148, v0
	v_add_f32_e32 v98, 1.0, v98
	v_rcp_f32_e32 v98, v98
	s_nop 0
	v_mul_f32_e32 v98, v101, v98
	v_mul_f32_e32 v0, v98, v0
	v_cvt_pk_bf16_f32 v0, v0, s0
	global_store_short v[122:123], v0, off offset:288
	s_nop 0
	v_ashrrev_i32_e32 v103, 31, v102
	v_lshlrev_b64 v[98:99], 8, v[102:103]
	v_lshl_add_u64 v[104:105], s[16:17], 0, v[98:99]
	global_load_dwordx4 v[114:117], v[104:105], off offset:16
	global_load_dwordx4 v[118:121], v[104:105], off
	v_mad_i64_i32 v[108:109], s[14:15], v102, s24, v[138:139]
	global_load_ushort v162, v[108:109], off
	global_load_ushort v163, v[108:109], off offset:32
	global_load_ushort v164, v[108:109], off offset:256
	global_load_ushort v165, v[108:109], off offset:288
	v_add_u32_e32 v98, 1, v102
	v_ashrrev_i32_e32 v99, 31, v98
	v_lshlrev_b64 v[100:101], 8, v[98:99]
	v_lshl_add_u64 v[100:101], s[16:17], 0, v[100:101]
	v_mad_i64_i32 v[110:111], s[14:15], v98, s24, v[138:139]
	global_load_ushort v166, v[110:111], off
	global_load_ushort v167, v[110:111], off offset:32
	global_load_ushort v168, v[110:111], off offset:256
	global_load_ushort v169, v[110:111], off offset:288
	v_add_u32_e32 v106, 2, v102
	v_ashrrev_i32_e32 v107, 31, v106
	v_lshlrev_b64 v[98:99], 8, v[106:107]
	v_lshl_add_u64 v[98:99], s[16:17], 0, v[98:99]
	v_mad_i64_i32 v[112:113], s[14:15], v106, s24, v[138:139]
	global_load_ushort v170, v[112:113], off
	global_load_ushort v171, v[112:113], off offset:32
	global_load_ushort v172, v[112:113], off offset:256
	global_load_ushort v173, v[112:113], off offset:288
	v_add_u32_e32 v106, 3, v102
	v_ashrrev_i32_e32 v107, 31, v106
	v_lshlrev_b64 v[102:103], 8, v[106:107]
	v_lshl_add_u64 v[102:103], s[16:17], 0, v[102:103]
	v_mad_i64_i32 v[106:107], s[14:15], v106, s24, v[138:139]
	global_load_ushort v174, v[106:107], off
	global_load_ushort v175, v[106:107], off offset:32
	global_load_ushort v176, v[106:107], off offset:256
	global_load_ushort v177, v[106:107], off offset:288
	s_waitcnt vmcnt(0)
	v_pk_add_f32 v[104:105], v[118:119], v[120:121]
	s_nop 0
	v_pk_add_f32 v[104:105], v[104:105], v[114:115]
	v_mul_f32_e32 v114, 0xbfb8aa3b, v94
	v_pk_add_f32 v[104:105], v[104:105], v[116:117]
	v_exp_f32_e32 v114, v114
	v_pk_mul_f32 v[104:105], v[104:105], s[18:19] op_sel_hi:[1,0]
	v_add_f32_e32 v114, 1.0, v114
	v_fma_f32 v0, -v104, v104, v105
	v_max_f32_e32 v0, 0, v0
	v_add_f32_e32 v0, 0x3727c5ac, v0
	v_cmp_gt_f32_e32 vcc, s25, v0
	v_mul_f32_e32 v105, 0x4b800000, v0
	v_rcp_f32_e32 v114, v114
	v_cndmask_b32_e32 v0, v0, v105, vcc
	v_rsq_f32_e32 v0, v0
	v_mul_f32_e32 v94, v94, v114
	v_mul_f32_e32 v114, 0xbfb8aa3b, v90
	v_mul_f32_e32 v105, 0x45800000, v0
	v_cndmask_b32_e32 v105, v0, v105, vcc
	v_exp_f32_e32 v114, v114
	s_waitcnt vmcnt(0)
	v_lshlrev_b32_e32 v0, 16, v162
	v_sub_f32_e32 v0, v0, v104
	v_mul_f32_e32 v0, v0, v105
	v_mul_f32_e32 v0, v151, v0
	v_mul_f32_e32 v0, v94, v0
	v_add_f32_e32 v114, 1.0, v114
	v_rcp_f32_e32 v114, v114
	v_cvt_pk_bf16_f32 v0, v0, s0
	v_mul_f32_e32 v90, v90, v114
	v_mul_f32_e32 v114, 0xbfb8aa3b, v86
	v_exp_f32_e32 v114, v114
	s_waitcnt vmcnt(0)
	v_lshlrev_b32_e32 v94, 16, v163
	v_sub_f32_e32 v94, v94, v104
	v_mul_f32_e32 v94, v94, v105
	v_mul_f32_e32 v94, v150, v94
	v_mul_f32_e32 v90, v90, v94
	v_add_f32_e32 v114, 1.0, v114
	v_rcp_f32_e32 v114, v114
	v_cvt_pk_bf16_f32 v90, v90, s0
	v_mul_f32_e32 v86, v86, v114
	s_waitcnt vmcnt(0)
	v_lshlrev_b32_e32 v94, 16, v164
	v_sub_f32_e32 v94, v94, v104
	v_mul_f32_e32 v94, v94, v105
	v_mul_f32_e32 v94, v149, v94
	v_mul_f32_e32 v86, v86, v94
	global_load_dwordx4 v[114:117], v[100:101], off offset:16
	global_load_dwordx4 v[118:121], v[100:101], off
	v_cvt_pk_bf16_f32 v86, v86, s0
	s_waitcnt vmcnt(0)
	v_lshlrev_b32_e32 v94, 16, v165
	v_sub_f32_e32 v94, v94, v104
	v_mul_f32_e32 v104, 0xbfb8aa3b, v82
	v_exp_f32_e32 v104, v104
	s_waitcnt vmcnt(0)
	v_pk_add_f32 v[100:101], v[118:119], v[120:121]
	v_mul_f32_e32 v94, v94, v105
	v_pk_add_f32 v[100:101], v[100:101], v[114:115]
	v_add_f32_e32 v104, 1.0, v104
	v_rcp_f32_e32 v104, v104
	v_mul_f32_e32 v94, v148, v94
	v_pk_add_f32 v[100:101], v[100:101], v[116:117]
	v_mul_f32_e32 v82, v82, v104
	v_mul_f32_e32 v82, v82, v94
	v_pk_mul_f32 v[100:101], v[100:101], s[18:19] op_sel_hi:[1,0]
	v_cvt_pk_bf16_f32 v94, v82, s0
	v_fma_f32 v82, -v100, v100, v101
	v_max_f32_e32 v82, 0, v82
	v_add_f32_e32 v82, 0x3727c5ac, v82
	v_cmp_gt_f32_e32 vcc, s25, v82
	v_mul_f32_e32 v101, 0x4b800000, v82
	v_mul_f32_e32 v104, 0xbfb8aa3b, v95
	v_cndmask_b32_e32 v82, v82, v101, vcc
	v_rsq_f32_e32 v82, v82
	v_exp_f32_e32 v104, v104
	v_mul_f32_e32 v101, 0x45800000, v82
	v_cndmask_b32_e32 v82, v82, v101, vcc
	v_add_f32_e32 v104, 1.0, v104
	v_rcp_f32_e32 v104, v104
	s_waitcnt vmcnt(0)
; __device__ __forceinline__ float bf2f(u16 b) { return __uint_as_float(((unsigned)b) << 16); }
; __device__ __forceinline__ float silu_f(float g) { return g * __builtin_amdgcn_rcpf(1.f + __builtin_amdgcn_exp2f(-g * LOG2E)); }
; template <int EPI>
; __device__ __forceinline__ void epilogue(const Params& p, int pass, int layer, int pm, int pn,
;                                          f32x4 (&acc)[2][2][4][2], const float* xin, float* xout) {
;     ...
;       for (int m = 0; m < 4; ++m) {
;         int tb = t0 + ai * 128 + wr * 64 + m * 16 + fq * 4;
;         asm volatile("" : "+v"(tb));
;         float4 s01[4], s23[4];
;         u16 yv[4][2][2];
; #pragma unroll
;         for (int j = 0; j < 4; ++j) {
;           const float4* sp = (const float4*)(stat + ((long)(tb + j) * 8 + h) * 8);
;           s01[j] = sp[0]; s23[j] = sp[1];
; #pragma unroll
;           for (int bj = 0; bj < 2; ++bj)
; #pragma unroll
;             for (int n = 0; n < 2; ++n)
;               yv[j][bj][n] = Y[(long)(tb + j) * YS + pn * 256 + bj * 128 + wc * 32 + n * 16 + fr];
;         }
; #pragma unroll
;         for (int j = 0; j < 4; ++j) {
;           float s1 = s01[j].x + s01[j].z + s23[j].x + s23[j].z, s2 = s01[j].y + s01[j].w + s23[j].y + s23[j].w;
;           float mu = s1 * (1.f / 512.f);
;           float var = s2 * (1.f / 512.f) - mu * mu;
;           float rstd = rsqrtf(fmaxf(var, 0.f) + 1e-5f);
; #pragma unroll
;           for (int bj = 0; bj < 2; ++bj)
; #pragma unroll
;             for (int n = 0; n < 2; ++n) {
;               float g = acc[ai][bj][m][n][j];
;               float yn = (bf2f(yv[j][bj][n]) - mu) * rstd * gn[bj][n];
;               Y[(long)(tb + j) * YS + pn * 256 + bj * 128 + wc * 32 + n * 16 + fr] = f2bf(silu_f(g) * yn);
;             }
;         }
	v_lshlrev_b32_e32 v101, 16, v166
	v_sub_f32_e32 v101, v101, v100
	v_mul_f32_e32 v101, v101, v82
	v_mul_f32_e32 v101, v151, v101
	v_mul_f32_e32 v95, v95, v104
	v_mul_f32_e32 v95, v95, v101
	v_mul_f32_e32 v104, 0xbfb8aa3b, v91
	v_exp_f32_e32 v104, v104
	v_cvt_pk_bf16_f32 v95, v95, s0
	v_add_f32_e32 v104, 1.0, v104
	v_rcp_f32_e32 v104, v104
	s_waitcnt vmcnt(0)
	v_lshlrev_b32_e32 v101, 16, v167
	v_sub_f32_e32 v101, v101, v100
	v_mul_f32_e32 v101, v101, v82
	v_mul_f32_e32 v101, v150, v101
	v_mul_f32_e32 v91, v91, v104
	v_mul_f32_e32 v91, v91, v101
	v_mul_f32_e32 v104, 0xbfb8aa3b, v87
	v_exp_f32_e32 v104, v104
	v_cvt_pk_bf16_f32 v91, v91, s0
	v_add_f32_e32 v104, 1.0, v104
	v_rcp_f32_e32 v104, v104
	s_waitcnt vmcnt(0)
	v_lshlrev_b32_e32 v101, 16, v168
	v_sub_f32_e32 v101, v101, v100
	v_mul_f32_e32 v101, v101, v82
	v_mul_f32_e32 v101, v149, v101
	v_mul_f32_e32 v87, v87, v104
	v_mul_f32_e32 v87, v87, v101
	v_cvt_pk_bf16_f32 v87, v87, s0
	s_waitcnt vmcnt(0)
	v_lshlrev_b32_e32 v101, 16, v169
	v_sub_f32_e32 v100, v101, v100
	v_mul_f32_e32 v82, v100, v82
	v_mul_f32_e32 v100, 0xbfb8aa3b, v83
	v_exp_f32_e32 v100, v100
	v_mul_f32_e32 v82, v148, v82
	v_add_f32_e32 v100, 1.0, v100
	v_rcp_f32_e32 v100, v100
	s_nop 0
	v_mul_f32_e32 v83, v83, v100
	global_load_dwordx4 v[116:119], v[98:99], off offset:16
	s_nop 0
	global_load_dwordx4 v[98:101], v[98:99], off
	v_mul_f32_e32 v82, v83, v82
	v_cvt_pk_bf16_f32 v114, v82, s0
	s_waitcnt vmcnt(0)
	v_pk_add_f32 v[82:83], v[98:99], v[100:101]
	s_nop 0
	v_pk_add_f32 v[82:83], v[82:83], v[116:117]
	v_mul_f32_e32 v99, 0xbfb8aa3b, v96
	v_pk_add_f32 v[82:83], v[82:83], v[118:119]
	v_exp_f32_e32 v99, v99
	v_pk_mul_f32 v[82:83], v[82:83], s[18:19] op_sel_hi:[1,0]
	v_add_f32_e32 v99, 1.0, v99
	v_fma_f32 v83, -v82, v82, v83
	v_max_f32_e32 v83, 0, v83
	v_add_f32_e32 v83, 0x3727c5ac, v83
	v_cmp_gt_f32_e32 vcc, s25, v83
	v_mul_f32_e32 v98, 0x4b800000, v83
	v_rcp_f32_e32 v99, v99
	v_cndmask_b32_e32 v83, v83, v98, vcc
	v_rsq_f32_e32 v83, v83
	v_mul_f32_e32 v96, v96, v99
	v_mul_f32_e32 v99, 0xbfb8aa3b, v92
	v_mul_f32_e32 v98, 0x45800000, v83
	v_cndmask_b32_e32 v98, v83, v98, vcc
	v_exp_f32_e32 v99, v99
	s_waitcnt vmcnt(0)
	v_lshlrev_b32_e32 v83, 16, v170
	v_sub_f32_e32 v83, v83, v82
	v_mul_f32_e32 v83, v83, v98
	v_mul_f32_e32 v83, v151, v83
	v_mul_f32_e32 v83, v96, v83
	v_add_f32_e32 v99, 1.0, v99
	v_rcp_f32_e32 v99, v99
	v_cvt_pk_bf16_f32 v83, v83, s0
	v_mul_f32_e32 v92, v92, v99
	v_mul_f32_e32 v99, 0xbfb8aa3b, v88
	v_exp_f32_e32 v99, v99
	s_waitcnt vmcnt(0)
	v_lshlrev_b32_e32 v96, 16, v171
	v_sub_f32_e32 v96, v96, v82
	v_mul_f32_e32 v96, v96, v98
	v_mul_f32_e32 v96, v150, v96
	v_mul_f32_e32 v92, v92, v96
	v_add_f32_e32 v99, 1.0, v99
	v_rcp_f32_e32 v99, v99
	v_cvt_pk_bf16_f32 v92, v92, s0
	v_mul_f32_e32 v88, v88, v99
	s_waitcnt vmcnt(0)
	v_lshlrev_b32_e32 v96, 16, v172
	v_sub_f32_e32 v96, v96, v82
	v_mul_f32_e32 v96, v96, v98
	v_mul_f32_e32 v96, v149, v96
	v_mul_f32_e32 v88, v88, v96
	v_cvt_pk_bf16_f32 v88, v88, s0
	s_waitcnt vmcnt(0)
	v_lshlrev_b32_e32 v96, 16, v173
	v_sub_f32_e32 v82, v96, v82
	v_mul_f32_e32 v96, 0xbfb8aa3b, v84
	v_exp_f32_e32 v96, v96
	v_mul_f32_e32 v82, v82, v98
	v_mul_f32_e32 v82, v148, v82
	v_add_f32_e32 v96, 1.0, v96
	v_rcp_f32_e32 v96, v96
	s_nop 0
	v_mul_f32_e32 v84, v84, v96
	v_mul_f32_e32 v82, v84, v82
	global_load_dwordx4 v[98:101], v[102:103], off offset:16
	s_nop 0
	global_load_dwordx4 v[102:105], v[102:103], off
	s_nop 0
	v_cvt_pk_bf16_f32 v82, v82, s0
	global_store_short v[108:109], v0, off
	global_store_short v[108:109], v90, off offset:32
	global_store_short v[108:109], v86, off offset:256
	global_store_short v[108:109], v94, off offset:288
	global_store_short v[110:111], v95, off
	global_store_short v[110:111], v91, off offset:32
	global_store_short v[110:111], v87, off offset:256
	global_store_short v[110:111], v114, off offset:288
	global_store_short v[112:113], v83, off
	global_store_short v[112:113], v92, off offset:32
	global_store_short v[112:113], v88, off offset:256
	global_store_short v[112:113], v82, off offset:288
	v_or_b32_e32 v86, 48, v152
	s_waitcnt vmcnt(0)
	v_pk_add_f32 v[82:83], v[102:103], v[104:105]
	s_nop 0
	v_pk_add_f32 v[82:83], v[82:83], v[98:99]
	s_nop 0
	v_pk_add_f32 v[82:83], v[82:83], v[100:101]
	s_nop 0
	v_pk_mul_f32 v[82:83], v[82:83], s[18:19] op_sel_hi:[1,0]
	s_nop 0
	v_fma_f32 v0, -v82, v82, v83
	v_max_f32_e32 v0, 0, v0
	v_add_f32_e32 v0, 0x3727c5ac, v0
	v_cmp_gt_f32_e32 vcc, s25, v0
	v_mul_f32_e32 v83, 0x4b800000, v0
	s_nop 0
	v_cndmask_b32_e32 v0, v0, v83, vcc
	v_rsq_f32_e32 v0, v0
	s_nop 0
	v_mul_f32_e32 v83, 0x45800000, v0
	v_cndmask_b32_e32 v0, v0, v83, vcc
	s_waitcnt vmcnt(0)
	v_lshlrev_b32_e32 v83, 16, v174
	v_mul_f32_e32 v84, 0xbfb8aa3b, v97
	v_exp_f32_e32 v84, v84
	v_sub_f32_e32 v83, v83, v82
	v_mul_f32_e32 v83, v83, v0
	v_mul_f32_e32 v83, v151, v83
	v_add_f32_e32 v84, 1.0, v84
	v_rcp_f32_e32 v84, v84
	s_nop 0
	v_mul_f32_e32 v84, v97, v84
	v_mul_f32_e32 v83, v84, v83
	v_mul_f32_e32 v84, 0xbfb8aa3b, v93
	v_exp_f32_e32 v84, v84
	v_cvt_pk_bf16_f32 v83, v83, s0
	global_store_short v[106:107], v83, off
	s_waitcnt vmcnt(0)
	v_lshlrev_b32_e32 v83, 16, v175
	v_add_f32_e32 v84, 1.0, v84
	v_rcp_f32_e32 v84, v84
	v_sub_f32_e32 v83, v83, v82
	v_mul_f32_e32 v83, v83, v0
	v_mul_f32_e32 v83, v150, v83
	v_mul_f32_e32 v84, v93, v84
	v_mul_f32_e32 v83, v84, v83
	v_mul_f32_e32 v84, 0xbfb8aa3b, v89
	v_exp_f32_e32 v84, v84
	v_cvt_pk_bf16_f32 v83, v83, s0
	global_store_short v[106:107], v83, off offset:32
	s_waitcnt vmcnt(0)
; __device__ __forceinline__ float bf2f(u16 b) { return __uint_as_float(((unsigned)b) << 16); }
; __device__ __forceinline__ float silu_f(float g) { return g * __builtin_amdgcn_rcpf(1.f + __builtin_amdgcn_exp2f(-g * LOG2E)); }
; template <int EPI>
; __device__ __forceinline__ void epilogue(const Params& p, int pass, int layer, int pm, int pn,
;                                          f32x4 (&acc)[2][2][4][2], const float* xin, float* xout) {
;     ...
;       for (int m = 0; m < 4; ++m) {
;         int tb = t0 + ai * 128 + wr * 64 + m * 16 + fq * 4;
;         asm volatile("" : "+v"(tb));
;         float4 s01[4], s23[4];
;         u16 yv[4][2][2];
; #pragma unroll
;         for (int j = 0; j < 4; ++j) {
;           const float4* sp = (const float4*)(stat + ((long)(tb + j) * 8 + h) * 8);
;           s01[j] = sp[0]; s23[j] = sp[1];
; #pragma unroll
;           for (int bj = 0; bj < 2; ++bj)
; #pragma unroll
;             for (int n = 0; n < 2; ++n)
;               yv[j][bj][n] = Y[(long)(tb + j) * YS + pn * 256 + bj * 128 + wc * 32 + n * 16 + fr];
;         }
; #pragma unroll
;         for (int j = 0; j < 4; ++j) {
;           float s1 = s01[j].x + s01[j].z + s23[j].x + s23[j].z, s2 = s01[j].y + s01[j].w + s23[j].y + s23[j].w;
;           float mu = s1 * (1.f / 512.f);
;           float var = s2 * (1.f / 512.f) - mu * mu;
;           float rstd = rsqrtf(fmaxf(var, 0.f) + 1e-5f);
; #pragma unroll
;           for (int bj = 0; bj < 2; ++bj)
; #pragma unroll
;             for (int n = 0; n < 2; ++n) {
;               float g = acc[ai][bj][m][n][j];
;               float yn = (bf2f(yv[j][bj][n]) - mu) * rstd * gn[bj][n];
;               Y[(long)(tb + j) * YS + pn * 256 + bj * 128 + wc * 32 + n * 16 + fr] = f2bf(silu_f(g) * yn);
;             }
;         }
	v_lshlrev_b32_e32 v83, 16, v176
	v_add_f32_e32 v84, 1.0, v84
	v_rcp_f32_e32 v84, v84
	v_sub_f32_e32 v83, v83, v82
	v_mul_f32_e32 v83, v83, v0
	v_mul_f32_e32 v83, v149, v83
	v_mul_f32_e32 v84, v89, v84
	v_mul_f32_e32 v83, v84, v83
	v_cvt_pk_bf16_f32 v83, v83, s0
	global_store_short v[106:107], v83, off offset:256
	s_waitcnt vmcnt(0)
	v_lshlrev_b32_e32 v83, 16, v177
	v_sub_f32_e32 v82, v83, v82
	v_mul_f32_e32 v0, v82, v0
	v_mul_f32_e32 v82, 0xbfb8aa3b, v85
	v_exp_f32_e32 v82, v82
	v_mul_f32_e32 v0, v148, v0
	v_add_f32_e32 v82, 1.0, v82
	v_rcp_f32_e32 v82, v82
	s_nop 0
	v_mul_f32_e32 v82, v85, v82
	v_mul_f32_e32 v0, v82, v0
	v_cvt_pk_bf16_f32 v0, v0, s0
	global_store_short v[106:107], v0, off offset:288
	s_nop 0
	v_ashrrev_i32_e32 v87, 31, v86
	v_lshlrev_b64 v[82:83], 8, v[86:87]
	v_lshl_add_u64 v[88:89], s[16:17], 0, v[82:83]
	global_load_dwordx4 v[98:101], v[88:89], off offset:16
	global_load_dwordx4 v[102:105], v[88:89], off
	v_mad_i64_i32 v[92:93], s[14:15], v86, s24, v[138:139]
	global_load_ushort v178, v[92:93], off
	global_load_ushort v179, v[92:93], off offset:32
	global_load_ushort v180, v[92:93], off offset:256
	global_load_ushort v181, v[92:93], off offset:288
	v_add_u32_e32 v82, 1, v86
	v_ashrrev_i32_e32 v83, 31, v82
	v_lshlrev_b64 v[84:85], 8, v[82:83]
	v_lshl_add_u64 v[84:85], s[16:17], 0, v[84:85]
	v_mad_i64_i32 v[94:95], s[14:15], v82, s24, v[138:139]
	global_load_ushort v182, v[94:95], off
	global_load_ushort v183, v[94:95], off offset:32
	global_load_ushort v184, v[94:95], off offset:256
	global_load_ushort v185, v[94:95], off offset:288
	v_add_u32_e32 v90, 2, v86
	v_ashrrev_i32_e32 v91, 31, v90
	v_lshlrev_b64 v[82:83], 8, v[90:91]
	v_lshl_add_u64 v[82:83], s[16:17], 0, v[82:83]
	v_mad_i64_i32 v[96:97], s[14:15], v90, s24, v[138:139]
	global_load_ushort v186, v[96:97], off
	global_load_ushort v187, v[96:97], off offset:32
	global_load_ushort v188, v[96:97], off offset:256
	global_load_ushort v189, v[96:97], off offset:288
	v_add_u32_e32 v90, 3, v86
	v_ashrrev_i32_e32 v91, 31, v90
	v_lshlrev_b64 v[86:87], 8, v[90:91]
	v_lshl_add_u64 v[86:87], s[16:17], 0, v[86:87]
	v_mad_i64_i32 v[90:91], s[14:15], v90, s24, v[138:139]
	global_load_ushort v190, v[90:91], off
	global_load_ushort v191, v[90:91], off offset:32
	global_load_ushort v192, v[90:91], off offset:256
	global_load_ushort v193, v[90:91], off offset:288
	s_waitcnt vmcnt(0)
	v_pk_add_f32 v[88:89], v[102:103], v[104:105]
	s_nop 0
	v_pk_add_f32 v[88:89], v[88:89], v[98:99]
	v_mul_f32_e32 v98, 0xbfb8aa3b, v78
	v_pk_add_f32 v[88:89], v[88:89], v[100:101]
	v_exp_f32_e32 v98, v98
	v_pk_mul_f32 v[88:89], v[88:89], s[18:19] op_sel_hi:[1,0]
	v_add_f32_e32 v98, 1.0, v98
	v_fma_f32 v0, -v88, v88, v89
	v_max_f32_e32 v0, 0, v0
	v_add_f32_e32 v0, 0x3727c5ac, v0
	v_cmp_gt_f32_e32 vcc, s25, v0
	v_mul_f32_e32 v89, 0x4b800000, v0
	v_rcp_f32_e32 v98, v98
	v_cndmask_b32_e32 v0, v0, v89, vcc
	v_rsq_f32_e32 v0, v0
	v_mul_f32_e32 v78, v78, v98
	v_mul_f32_e32 v98, 0xbfb8aa3b, v74
	v_mul_f32_e32 v89, 0x45800000, v0
	v_cndmask_b32_e32 v89, v0, v89, vcc
	v_exp_f32_e32 v98, v98
	s_waitcnt vmcnt(0)
	v_lshlrev_b32_e32 v0, 16, v178
	v_sub_f32_e32 v0, v0, v88
	v_mul_f32_e32 v0, v0, v89
	v_mul_f32_e32 v0, v151, v0
	v_mul_f32_e32 v0, v78, v0
	v_add_f32_e32 v98, 1.0, v98
	v_rcp_f32_e32 v98, v98
	v_cvt_pk_bf16_f32 v0, v0, s0
	v_mul_f32_e32 v74, v74, v98
	v_mul_f32_e32 v98, 0xbfb8aa3b, v70
	v_exp_f32_e32 v98, v98
	s_waitcnt vmcnt(0)
	v_lshlrev_b32_e32 v78, 16, v179
	v_sub_f32_e32 v78, v78, v88
	v_mul_f32_e32 v78, v78, v89
	v_mul_f32_e32 v78, v150, v78
	v_mul_f32_e32 v74, v74, v78
	v_add_f32_e32 v98, 1.0, v98
	v_rcp_f32_e32 v98, v98
	v_cvt_pk_bf16_f32 v74, v74, s0
	v_mul_f32_e32 v70, v70, v98
	s_waitcnt vmcnt(0)
	v_lshlrev_b32_e32 v78, 16, v180
	v_sub_f32_e32 v78, v78, v88
	v_mul_f32_e32 v78, v78, v89
	v_mul_f32_e32 v78, v149, v78
	v_mul_f32_e32 v70, v70, v78
	global_load_dwordx4 v[98:101], v[84:85], off offset:16
	global_load_dwordx4 v[102:105], v[84:85], off
	v_cvt_pk_bf16_f32 v70, v70, s0
	s_waitcnt vmcnt(0)
	v_lshlrev_b32_e32 v78, 16, v181
	v_sub_f32_e32 v78, v78, v88
	v_mul_f32_e32 v88, 0xbfb8aa3b, v66
	v_exp_f32_e32 v88, v88
	s_waitcnt vmcnt(0)
	v_pk_add_f32 v[84:85], v[102:103], v[104:105]
	v_mul_f32_e32 v78, v78, v89
	v_pk_add_f32 v[84:85], v[84:85], v[98:99]
	v_add_f32_e32 v88, 1.0, v88
	v_rcp_f32_e32 v88, v88
	v_mul_f32_e32 v78, v148, v78
	v_pk_add_f32 v[84:85], v[84:85], v[100:101]
	v_mul_f32_e32 v66, v66, v88
	v_mul_f32_e32 v66, v66, v78
	v_pk_mul_f32 v[84:85], v[84:85], s[18:19] op_sel_hi:[1,0]
	v_cvt_pk_bf16_f32 v78, v66, s0
	v_fma_f32 v66, -v84, v84, v85
	v_max_f32_e32 v66, 0, v66
	v_add_f32_e32 v66, 0x3727c5ac, v66
	v_cmp_gt_f32_e32 vcc, s25, v66
	v_mul_f32_e32 v85, 0x4b800000, v66
	v_mul_f32_e32 v88, 0xbfb8aa3b, v79
	v_cndmask_b32_e32 v66, v66, v85, vcc
	v_rsq_f32_e32 v66, v66
	v_exp_f32_e32 v88, v88
	v_mul_f32_e32 v85, 0x45800000, v66
	v_cndmask_b32_e32 v66, v66, v85, vcc
	v_add_f32_e32 v88, 1.0, v88
	v_rcp_f32_e32 v88, v88
	s_waitcnt vmcnt(0)
	v_lshlrev_b32_e32 v85, 16, v182
	v_sub_f32_e32 v85, v85, v84
	v_mul_f32_e32 v85, v85, v66
	v_mul_f32_e32 v85, v151, v85
	v_mul_f32_e32 v79, v79, v88
	v_mul_f32_e32 v79, v79, v85
	v_mul_f32_e32 v88, 0xbfb8aa3b, v75
	v_exp_f32_e32 v88, v88
	v_cvt_pk_bf16_f32 v79, v79, s0
	v_add_f32_e32 v88, 1.0, v88
	v_rcp_f32_e32 v88, v88
	s_waitcnt vmcnt(0)
	v_lshlrev_b32_e32 v85, 16, v183
	v_sub_f32_e32 v85, v85, v84
	v_mul_f32_e32 v85, v85, v66
	v_mul_f32_e32 v85, v150, v85
	v_mul_f32_e32 v75, v75, v88
	v_mul_f32_e32 v75, v75, v85
	v_mul_f32_e32 v88, 0xbfb8aa3b, v71
	v_exp_f32_e32 v88, v88
	v_cvt_pk_bf16_f32 v75, v75, s0
	v_add_f32_e32 v88, 1.0, v88
	v_rcp_f32_e32 v88, v88
	s_waitcnt vmcnt(0)
; __device__ __forceinline__ float bf2f(u16 b) { return __uint_as_float(((unsigned)b) << 16); }
; __device__ __forceinline__ float silu_f(float g) { return g * __builtin_amdgcn_rcpf(1.f + __builtin_amdgcn_exp2f(-g * LOG2E)); }
; template <int EPI>
; __device__ __forceinline__ void epilogue(const Params& p, int pass, int layer, int pm, int pn,
;                                          f32x4 (&acc)[2][2][4][2], const float* xin, float* xout) {
;     ...
;       for (int m = 0; m < 4; ++m) {
;         int tb = t0 + ai * 128 + wr * 64 + m * 16 + fq * 4;
;         asm volatile("" : "+v"(tb));
;         float4 s01[4], s23[4];
;         u16 yv[4][2][2];
; #pragma unroll
;         for (int j = 0; j < 4; ++j) {
;           const float4* sp = (const float4*)(stat + ((long)(tb + j) * 8 + h) * 8);
;           s01[j] = sp[0]; s23[j] = sp[1];
; #pragma unroll
;           for (int bj = 0; bj < 2; ++bj)
; #pragma unroll
;             for (int n = 0; n < 2; ++n)
;               yv[j][bj][n] = Y[(long)(tb + j) * YS + pn * 256 + bj * 128 + wc * 32 + n * 16 + fr];
;         }
; #pragma unroll
;         for (int j = 0; j < 4; ++j) {
;           float s1 = s01[j].x + s01[j].z + s23[j].x + s23[j].z, s2 = s01[j].y + s01[j].w + s23[j].y + s23[j].w;
;           float mu = s1 * (1.f / 512.f);
;           float var = s2 * (1.f / 512.f) - mu * mu;
;           float rstd = rsqrtf(fmaxf(var, 0.f) + 1e-5f);
; #pragma unroll
;           for (int bj = 0; bj < 2; ++bj)
; #pragma unroll
;             for (int n = 0; n < 2; ++n) {
;               float g = acc[ai][bj][m][n][j];
;               float yn = (bf2f(yv[j][bj][n]) - mu) * rstd * gn[bj][n];
;               Y[(long)(tb + j) * YS + pn * 256 + bj * 128 + wc * 32 + n * 16 + fr] = f2bf(silu_f(g) * yn);
;             }
;         }
	v_lshlrev_b32_e32 v85, 16, v184
	v_sub_f32_e32 v85, v85, v84
	v_mul_f32_e32 v85, v85, v66
	v_mul_f32_e32 v85, v149, v85
	v_mul_f32_e32 v71, v71, v88
	v_mul_f32_e32 v71, v71, v85
	v_cvt_pk_bf16_f32 v71, v71, s0
	s_waitcnt vmcnt(0)
	v_lshlrev_b32_e32 v85, 16, v185
	v_sub_f32_e32 v84, v85, v84
	v_mul_f32_e32 v66, v84, v66
	v_mul_f32_e32 v84, 0xbfb8aa3b, v67
	v_exp_f32_e32 v84, v84
	v_mul_f32_e32 v66, v148, v66
	v_add_f32_e32 v84, 1.0, v84
	v_rcp_f32_e32 v84, v84
	s_nop 0
	v_mul_f32_e32 v67, v67, v84
	global_load_dwordx4 v[100:103], v[82:83], off offset:16
	s_nop 0
	global_load_dwordx4 v[82:85], v[82:83], off
	v_mul_f32_e32 v66, v67, v66
	v_cvt_pk_bf16_f32 v98, v66, s0
	s_waitcnt vmcnt(0)
	v_pk_add_f32 v[66:67], v[82:83], v[84:85]
	s_nop 0
	v_pk_add_f32 v[66:67], v[66:67], v[100:101]
	v_mul_f32_e32 v83, 0xbfb8aa3b, v80
	v_pk_add_f32 v[66:67], v[66:67], v[102:103]
	v_exp_f32_e32 v83, v83
	v_pk_mul_f32 v[66:67], v[66:67], s[18:19] op_sel_hi:[1,0]
	v_add_f32_e32 v83, 1.0, v83
	v_fma_f32 v67, -v66, v66, v67
	v_max_f32_e32 v67, 0, v67
	v_add_f32_e32 v67, 0x3727c5ac, v67
	v_cmp_gt_f32_e32 vcc, s25, v67
	v_mul_f32_e32 v82, 0x4b800000, v67
	v_rcp_f32_e32 v83, v83
	v_cndmask_b32_e32 v67, v67, v82, vcc
	v_rsq_f32_e32 v67, v67
	v_mul_f32_e32 v80, v80, v83
	v_mul_f32_e32 v83, 0xbfb8aa3b, v76
	v_mul_f32_e32 v82, 0x45800000, v67
	v_cndmask_b32_e32 v82, v67, v82, vcc
	v_exp_f32_e32 v83, v83
	s_waitcnt vmcnt(0)
	v_lshlrev_b32_e32 v67, 16, v186
	v_sub_f32_e32 v67, v67, v66
	v_mul_f32_e32 v67, v67, v82
	v_mul_f32_e32 v67, v151, v67
	v_mul_f32_e32 v67, v80, v67
	v_add_f32_e32 v83, 1.0, v83
	v_rcp_f32_e32 v83, v83
	v_cvt_pk_bf16_f32 v67, v67, s0
	v_mul_f32_e32 v76, v76, v83
	v_mul_f32_e32 v83, 0xbfb8aa3b, v72
	v_exp_f32_e32 v83, v83
	s_waitcnt vmcnt(0)
	v_lshlrev_b32_e32 v80, 16, v187
	v_sub_f32_e32 v80, v80, v66
	v_mul_f32_e32 v80, v80, v82
	v_mul_f32_e32 v80, v150, v80
	v_mul_f32_e32 v76, v76, v80
	v_add_f32_e32 v83, 1.0, v83
	v_rcp_f32_e32 v83, v83
	v_cvt_pk_bf16_f32 v76, v76, s0
	v_mul_f32_e32 v72, v72, v83
	s_waitcnt vmcnt(0)
	v_lshlrev_b32_e32 v80, 16, v188
	v_sub_f32_e32 v80, v80, v66
	v_mul_f32_e32 v80, v80, v82
	v_mul_f32_e32 v80, v149, v80
	v_mul_f32_e32 v72, v72, v80
	v_cvt_pk_bf16_f32 v72, v72, s0
	s_waitcnt vmcnt(0)
	v_lshlrev_b32_e32 v80, 16, v189
	v_sub_f32_e32 v66, v80, v66
	v_mul_f32_e32 v80, 0xbfb8aa3b, v68
	v_exp_f32_e32 v80, v80
	v_mul_f32_e32 v66, v66, v82
	v_mul_f32_e32 v66, v148, v66
	v_add_f32_e32 v80, 1.0, v80
	v_rcp_f32_e32 v80, v80
	s_nop 0
	v_mul_f32_e32 v68, v68, v80
	v_mul_f32_e32 v66, v68, v66
	global_load_dwordx4 v[82:85], v[86:87], off offset:16
	s_nop 0
	global_load_dwordx4 v[86:89], v[86:87], off
	s_nop 0
	v_cvt_pk_bf16_f32 v66, v66, s0
	global_store_short v[92:93], v0, off
	global_store_short v[92:93], v74, off offset:32
	global_store_short v[92:93], v70, off offset:256
	global_store_short v[92:93], v78, off offset:288
	global_store_short v[94:95], v79, off
	global_store_short v[94:95], v75, off offset:32
	global_store_short v[94:95], v71, off offset:256
	global_store_short v[94:95], v98, off offset:288
	global_store_short v[96:97], v67, off
	global_store_short v[96:97], v76, off offset:32
	global_store_short v[96:97], v72, off offset:256
	global_store_short v[96:97], v66, off offset:288
	v_add_u32_e32 v70, 0x80, v152
	s_waitcnt vmcnt(0)
	v_pk_add_f32 v[66:67], v[86:87], v[88:89]
	s_nop 0
	v_pk_add_f32 v[66:67], v[66:67], v[82:83]
	s_nop 0
	v_pk_add_f32 v[66:67], v[66:67], v[84:85]
	s_nop 0
	v_pk_mul_f32 v[66:67], v[66:67], s[18:19] op_sel_hi:[1,0]
	s_nop 0
	v_fma_f32 v0, -v66, v66, v67
	v_max_f32_e32 v0, 0, v0
	v_add_f32_e32 v0, 0x3727c5ac, v0
	v_cmp_gt_f32_e32 vcc, s25, v0
	v_mul_f32_e32 v67, 0x4b800000, v0
	s_nop 0
	v_cndmask_b32_e32 v0, v0, v67, vcc
	v_rsq_f32_e32 v0, v0
	s_nop 0
	v_mul_f32_e32 v67, 0x45800000, v0
	v_cndmask_b32_e32 v0, v0, v67, vcc
	s_waitcnt vmcnt(0)
	v_lshlrev_b32_e32 v67, 16, v190
	v_mul_f32_e32 v68, 0xbfb8aa3b, v81
	v_exp_f32_e32 v68, v68
	v_sub_f32_e32 v67, v67, v66
	v_mul_f32_e32 v67, v67, v0
	v_mul_f32_e32 v67, v151, v67
	v_add_f32_e32 v68, 1.0, v68
	v_rcp_f32_e32 v68, v68
	s_nop 0
	v_mul_f32_e32 v68, v81, v68
	v_mul_f32_e32 v67, v68, v67
	v_mul_f32_e32 v68, 0xbfb8aa3b, v77
	v_exp_f32_e32 v68, v68
	v_cvt_pk_bf16_f32 v67, v67, s0
	global_store_short v[90:91], v67, off
	s_waitcnt vmcnt(0)
	v_lshlrev_b32_e32 v67, 16, v191
	v_add_f32_e32 v68, 1.0, v68
	v_rcp_f32_e32 v68, v68
	v_sub_f32_e32 v67, v67, v66
	v_mul_f32_e32 v67, v67, v0
	v_mul_f32_e32 v67, v150, v67
	v_mul_f32_e32 v68, v77, v68
	v_mul_f32_e32 v67, v68, v67
	v_mul_f32_e32 v68, 0xbfb8aa3b, v73
	v_exp_f32_e32 v68, v68
	v_cvt_pk_bf16_f32 v67, v67, s0
	global_store_short v[90:91], v67, off offset:32
	s_waitcnt vmcnt(0)
	v_lshlrev_b32_e32 v67, 16, v192
	v_add_f32_e32 v68, 1.0, v68
	v_rcp_f32_e32 v68, v68
	v_sub_f32_e32 v67, v67, v66
	v_mul_f32_e32 v67, v67, v0
	v_mul_f32_e32 v67, v149, v67
	v_mul_f32_e32 v68, v73, v68
	v_mul_f32_e32 v67, v68, v67
	v_cvt_pk_bf16_f32 v67, v67, s0
	global_store_short v[90:91], v67, off offset:256
	s_waitcnt vmcnt(0)
; __device__ __forceinline__ float bf2f(u16 b) { return __uint_as_float(((unsigned)b) << 16); }
; __device__ __forceinline__ float silu_f(float g) { return g * __builtin_amdgcn_rcpf(1.f + __builtin_amdgcn_exp2f(-g * LOG2E)); }
; template <int EPI>
; __device__ __forceinline__ void epilogue(const Params& p, int pass, int layer, int pm, int pn,
;                                          f32x4 (&acc)[2][2][4][2], const float* xin, float* xout) {
;     ...
;       for (int m = 0; m < 4; ++m) {
;         int tb = t0 + ai * 128 + wr * 64 + m * 16 + fq * 4;
;         asm volatile("" : "+v"(tb));
;         float4 s01[4], s23[4];
;         u16 yv[4][2][2];
; #pragma unroll
;         for (int j = 0; j < 4; ++j) {
;           const float4* sp = (const float4*)(stat + ((long)(tb + j) * 8 + h) * 8);
;           s01[j] = sp[0]; s23[j] = sp[1];
; #pragma unroll
;           for (int bj = 0; bj < 2; ++bj)
; #pragma unroll
;             for (int n = 0; n < 2; ++n)
;               yv[j][bj][n] = Y[(long)(tb + j) * YS + pn * 256 + bj * 128 + wc * 32 + n * 16 + fr];
;         }
; #pragma unroll
;         for (int j = 0; j < 4; ++j) {
;           float s1 = s01[j].x + s01[j].z + s23[j].x + s23[j].z, s2 = s01[j].y + s01[j].w + s23[j].y + s23[j].w;
;           float mu = s1 * (1.f / 512.f);
;           float var = s2 * (1.f / 512.f) - mu * mu;
;           float rstd = rsqrtf(fmaxf(var, 0.f) + 1e-5f);
; #pragma unroll
;           for (int bj = 0; bj < 2; ++bj)
; #pragma unroll
;             for (int n = 0; n < 2; ++n) {
;               float g = acc[ai][bj][m][n][j];
;               float yn = (bf2f(yv[j][bj][n]) - mu) * rstd * gn[bj][n];
;               Y[(long)(tb + j) * YS + pn * 256 + bj * 128 + wc * 32 + n * 16 + fr] = f2bf(silu_f(g) * yn);
;             }
;         }
	v_lshlrev_b32_e32 v67, 16, v193
	v_sub_f32_e32 v66, v67, v66
	v_mul_f32_e32 v0, v66, v0
	v_mul_f32_e32 v66, 0xbfb8aa3b, v69
	v_exp_f32_e32 v66, v66
	v_mul_f32_e32 v0, v148, v0
	v_add_f32_e32 v66, 1.0, v66
	v_rcp_f32_e32 v66, v66
	s_nop 0
	v_mul_f32_e32 v66, v69, v66
	v_mul_f32_e32 v0, v66, v0
	v_cvt_pk_bf16_f32 v0, v0, s0
	global_store_short v[90:91], v0, off offset:288
	s_nop 0
	v_ashrrev_i32_e32 v71, 31, v70
	v_lshlrev_b64 v[66:67], 8, v[70:71]
	v_lshl_add_u64 v[72:73], s[16:17], 0, v[66:67]
	global_load_dwordx4 v[82:85], v[72:73], off offset:16
	global_load_dwordx4 v[86:89], v[72:73], off
	v_mad_i64_i32 v[76:77], s[14:15], v70, s24, v[138:139]
	global_load_ushort v162, v[76:77], off
	global_load_ushort v163, v[76:77], off offset:32
	global_load_ushort v164, v[76:77], off offset:256
	global_load_ushort v165, v[76:77], off offset:288
	v_add_u32_e32 v66, 1, v70
	v_ashrrev_i32_e32 v67, 31, v66
	v_lshlrev_b64 v[68:69], 8, v[66:67]
	v_lshl_add_u64 v[68:69], s[16:17], 0, v[68:69]
	v_mad_i64_i32 v[78:79], s[14:15], v66, s24, v[138:139]
	global_load_ushort v166, v[78:79], off
	global_load_ushort v167, v[78:79], off offset:32
	global_load_ushort v168, v[78:79], off offset:256
	global_load_ushort v169, v[78:79], off offset:288
	v_add_u32_e32 v74, 2, v70
	v_ashrrev_i32_e32 v75, 31, v74
	v_lshlrev_b64 v[66:67], 8, v[74:75]
	v_lshl_add_u64 v[66:67], s[16:17], 0, v[66:67]
	v_mad_i64_i32 v[80:81], s[14:15], v74, s24, v[138:139]
	global_load_ushort v170, v[80:81], off
	global_load_ushort v171, v[80:81], off offset:32
	global_load_ushort v172, v[80:81], off offset:256
	global_load_ushort v173, v[80:81], off offset:288
	v_add_u32_e32 v74, 3, v70
	v_ashrrev_i32_e32 v75, 31, v74
	v_lshlrev_b64 v[70:71], 8, v[74:75]
	v_lshl_add_u64 v[70:71], s[16:17], 0, v[70:71]
	v_mad_i64_i32 v[74:75], s[14:15], v74, s24, v[138:139]
	global_load_ushort v174, v[74:75], off
	global_load_ushort v175, v[74:75], off offset:32
	global_load_ushort v176, v[74:75], off offset:256
	global_load_ushort v177, v[74:75], off offset:288
	s_waitcnt vmcnt(0)
	v_pk_add_f32 v[72:73], v[86:87], v[88:89]
	s_nop 0
	v_pk_add_f32 v[72:73], v[72:73], v[82:83]
	v_mul_f32_e32 v82, 0xbfb8aa3b, v62
	v_pk_add_f32 v[72:73], v[72:73], v[84:85]
	v_exp_f32_e32 v82, v82
	v_pk_mul_f32 v[72:73], v[72:73], s[18:19] op_sel_hi:[1,0]
	v_add_f32_e32 v82, 1.0, v82
	v_fma_f32 v0, -v72, v72, v73
	v_max_f32_e32 v0, 0, v0
	v_add_f32_e32 v0, 0x3727c5ac, v0
	v_cmp_gt_f32_e32 vcc, s25, v0
	v_mul_f32_e32 v73, 0x4b800000, v0
	v_rcp_f32_e32 v82, v82
	v_cndmask_b32_e32 v0, v0, v73, vcc
	v_rsq_f32_e32 v0, v0
	v_mul_f32_e32 v62, v62, v82
	v_mul_f32_e32 v82, 0xbfb8aa3b, v58
	v_mul_f32_e32 v73, 0x45800000, v0
	v_cndmask_b32_e32 v73, v0, v73, vcc
	v_exp_f32_e32 v82, v82
	s_waitcnt vmcnt(0)
	v_lshlrev_b32_e32 v0, 16, v162
	v_sub_f32_e32 v0, v0, v72
	v_mul_f32_e32 v0, v0, v73
	v_mul_f32_e32 v0, v151, v0
	v_mul_f32_e32 v0, v62, v0
	v_add_f32_e32 v82, 1.0, v82
	v_rcp_f32_e32 v82, v82
	v_cvt_pk_bf16_f32 v0, v0, s0
	v_mul_f32_e32 v58, v58, v82
	v_mul_f32_e32 v82, 0xbfb8aa3b, v54
	v_exp_f32_e32 v82, v82
	s_waitcnt vmcnt(0)
	v_lshlrev_b32_e32 v62, 16, v163
	v_sub_f32_e32 v62, v62, v72
	v_mul_f32_e32 v62, v62, v73
	v_mul_f32_e32 v62, v150, v62
	v_mul_f32_e32 v58, v58, v62
	v_add_f32_e32 v82, 1.0, v82
	v_rcp_f32_e32 v82, v82
	v_cvt_pk_bf16_f32 v58, v58, s0
	v_mul_f32_e32 v54, v54, v82
	s_waitcnt vmcnt(0)
	v_lshlrev_b32_e32 v62, 16, v164
	v_sub_f32_e32 v62, v62, v72
	v_mul_f32_e32 v62, v62, v73
	v_mul_f32_e32 v62, v149, v62
	v_mul_f32_e32 v54, v54, v62
	global_load_dwordx4 v[82:85], v[68:69], off offset:16
	global_load_dwordx4 v[86:89], v[68:69], off
	v_cvt_pk_bf16_f32 v54, v54, s0
	s_waitcnt vmcnt(0)
	v_lshlrev_b32_e32 v62, 16, v165
	v_sub_f32_e32 v62, v62, v72
	v_mul_f32_e32 v72, 0xbfb8aa3b, v50
	v_exp_f32_e32 v72, v72
	s_waitcnt vmcnt(0)
	v_pk_add_f32 v[68:69], v[86:87], v[88:89]
	v_mul_f32_e32 v62, v62, v73
	v_pk_add_f32 v[68:69], v[68:69], v[82:83]
	v_add_f32_e32 v72, 1.0, v72
	v_rcp_f32_e32 v72, v72
	v_mul_f32_e32 v62, v148, v62
	v_pk_add_f32 v[68:69], v[68:69], v[84:85]
	v_mul_f32_e32 v50, v50, v72
	v_mul_f32_e32 v50, v50, v62
	v_pk_mul_f32 v[68:69], v[68:69], s[18:19] op_sel_hi:[1,0]
	v_cvt_pk_bf16_f32 v62, v50, s0
	v_fma_f32 v50, -v68, v68, v69
	v_max_f32_e32 v50, 0, v50
	v_add_f32_e32 v50, 0x3727c5ac, v50
	v_cmp_gt_f32_e32 vcc, s25, v50
	v_mul_f32_e32 v69, 0x4b800000, v50
	v_mul_f32_e32 v72, 0xbfb8aa3b, v63
	v_cndmask_b32_e32 v50, v50, v69, vcc
	v_rsq_f32_e32 v50, v50
	v_exp_f32_e32 v72, v72
	v_mul_f32_e32 v69, 0x45800000, v50
	v_cndmask_b32_e32 v50, v50, v69, vcc
	v_add_f32_e32 v72, 1.0, v72
	v_rcp_f32_e32 v72, v72
	s_waitcnt vmcnt(0)
	v_lshlrev_b32_e32 v69, 16, v166
	v_sub_f32_e32 v69, v69, v68
	v_mul_f32_e32 v69, v69, v50
	v_mul_f32_e32 v69, v151, v69
	v_mul_f32_e32 v63, v63, v72
	v_mul_f32_e32 v63, v63, v69
	v_mul_f32_e32 v72, 0xbfb8aa3b, v59
	v_exp_f32_e32 v72, v72
	v_cvt_pk_bf16_f32 v63, v63, s0
	v_add_f32_e32 v72, 1.0, v72
	v_rcp_f32_e32 v72, v72
	s_waitcnt vmcnt(0)
	v_lshlrev_b32_e32 v69, 16, v167
	v_sub_f32_e32 v69, v69, v68
	v_mul_f32_e32 v69, v69, v50
	v_mul_f32_e32 v69, v150, v69
	v_mul_f32_e32 v59, v59, v72
	v_mul_f32_e32 v59, v59, v69
	v_mul_f32_e32 v72, 0xbfb8aa3b, v55
	v_exp_f32_e32 v72, v72
	v_cvt_pk_bf16_f32 v59, v59, s0
	v_add_f32_e32 v72, 1.0, v72
	v_rcp_f32_e32 v72, v72
	s_waitcnt vmcnt(0)
	v_lshlrev_b32_e32 v69, 16, v168
	v_sub_f32_e32 v69, v69, v68
	v_mul_f32_e32 v69, v69, v50
	v_mul_f32_e32 v69, v149, v69
	v_mul_f32_e32 v55, v55, v72
	v_mul_f32_e32 v55, v55, v69
	v_cvt_pk_bf16_f32 v55, v55, s0
	s_waitcnt vmcnt(0)
; __device__ __forceinline__ float bf2f(u16 b) { return __uint_as_float(((unsigned)b) << 16); }
; __device__ __forceinline__ float silu_f(float g) { return g * __builtin_amdgcn_rcpf(1.f + __builtin_amdgcn_exp2f(-g * LOG2E)); }
; template <int EPI>
; __device__ __forceinline__ void epilogue(const Params& p, int pass, int layer, int pm, int pn,
;                                          f32x4 (&acc)[2][2][4][2], const float* xin, float* xout) {
;     ...
;       for (int m = 0; m < 4; ++m) {
;         int tb = t0 + ai * 128 + wr * 64 + m * 16 + fq * 4;
;         asm volatile("" : "+v"(tb));
;         float4 s01[4], s23[4];
;         u16 yv[4][2][2];
; #pragma unroll
;         for (int j = 0; j < 4; ++j) {
;           const float4* sp = (const float4*)(stat + ((long)(tb + j) * 8 + h) * 8);
;           s01[j] = sp[0]; s23[j] = sp[1];
; #pragma unroll
;           for (int bj = 0; bj < 2; ++bj)
; #pragma unroll
;             for (int n = 0; n < 2; ++n)
;               yv[j][bj][n] = Y[(long)(tb + j) * YS + pn * 256 + bj * 128 + wc * 32 + n * 16 + fr];
;         }
; #pragma unroll
;         for (int j = 0; j < 4; ++j) {
;           float s1 = s01[j].x + s01[j].z + s23[j].x + s23[j].z, s2 = s01[j].y + s01[j].w + s23[j].y + s23[j].w;
;           float mu = s1 * (1.f / 512.f);
;           float var = s2 * (1.f / 512.f) - mu * mu;
;           float rstd = rsqrtf(fmaxf(var, 0.f) + 1e-5f);
; #pragma unroll
;           for (int bj = 0; bj < 2; ++bj)
; #pragma unroll
;             for (int n = 0; n < 2; ++n) {
;               float g = acc[ai][bj][m][n][j];
;               float yn = (bf2f(yv[j][bj][n]) - mu) * rstd * gn[bj][n];
;               Y[(long)(tb + j) * YS + pn * 256 + bj * 128 + wc * 32 + n * 16 + fr] = f2bf(silu_f(g) * yn);
;             }
;         }
	v_lshlrev_b32_e32 v69, 16, v169
	v_sub_f32_e32 v68, v69, v68
	v_mul_f32_e32 v50, v68, v50
	v_mul_f32_e32 v68, 0xbfb8aa3b, v51
	v_exp_f32_e32 v68, v68
	v_mul_f32_e32 v50, v148, v50
	v_add_f32_e32 v68, 1.0, v68
	v_rcp_f32_e32 v68, v68
	s_nop 0
	v_mul_f32_e32 v51, v51, v68
	global_load_dwordx4 v[84:87], v[66:67], off offset:16
	s_nop 0
	global_load_dwordx4 v[66:69], v[66:67], off
	v_mul_f32_e32 v50, v51, v50
	v_cvt_pk_bf16_f32 v82, v50, s0
	s_waitcnt vmcnt(0)
	v_pk_add_f32 v[50:51], v[66:67], v[68:69]
	s_nop 0
	v_pk_add_f32 v[50:51], v[50:51], v[84:85]
	v_mul_f32_e32 v67, 0xbfb8aa3b, v64
	v_pk_add_f32 v[50:51], v[50:51], v[86:87]
	v_exp_f32_e32 v67, v67
	v_pk_mul_f32 v[50:51], v[50:51], s[18:19] op_sel_hi:[1,0]
	v_add_f32_e32 v67, 1.0, v67
	v_fma_f32 v51, -v50, v50, v51
	v_max_f32_e32 v51, 0, v51
	v_add_f32_e32 v51, 0x3727c5ac, v51
	v_cmp_gt_f32_e32 vcc, s25, v51
	v_mul_f32_e32 v66, 0x4b800000, v51
	v_rcp_f32_e32 v67, v67
	v_cndmask_b32_e32 v51, v51, v66, vcc
	v_rsq_f32_e32 v51, v51
	v_mul_f32_e32 v64, v64, v67
	v_mul_f32_e32 v67, 0xbfb8aa3b, v60
	v_mul_f32_e32 v66, 0x45800000, v51
	v_cndmask_b32_e32 v66, v51, v66, vcc
	v_exp_f32_e32 v67, v67
	s_waitcnt vmcnt(0)
	v_lshlrev_b32_e32 v51, 16, v170
	v_sub_f32_e32 v51, v51, v50
	v_mul_f32_e32 v51, v51, v66
	v_mul_f32_e32 v51, v151, v51
	v_mul_f32_e32 v51, v64, v51
	v_add_f32_e32 v67, 1.0, v67
	v_rcp_f32_e32 v67, v67
	v_cvt_pk_bf16_f32 v51, v51, s0
	v_mul_f32_e32 v60, v60, v67
	v_mul_f32_e32 v67, 0xbfb8aa3b, v56
	v_exp_f32_e32 v67, v67
	s_waitcnt vmcnt(0)
	v_lshlrev_b32_e32 v64, 16, v171
	v_sub_f32_e32 v64, v64, v50
	v_mul_f32_e32 v64, v64, v66
	v_mul_f32_e32 v64, v150, v64
	v_mul_f32_e32 v60, v60, v64
	v_add_f32_e32 v67, 1.0, v67
	v_rcp_f32_e32 v67, v67
	v_cvt_pk_bf16_f32 v60, v60, s0
	v_mul_f32_e32 v56, v56, v67
	s_waitcnt vmcnt(0)
	v_lshlrev_b32_e32 v64, 16, v172
	v_sub_f32_e32 v64, v64, v50
	v_mul_f32_e32 v64, v64, v66
	v_mul_f32_e32 v64, v149, v64
	v_mul_f32_e32 v56, v56, v64
	v_cvt_pk_bf16_f32 v56, v56, s0
	s_waitcnt vmcnt(0)
	v_lshlrev_b32_e32 v64, 16, v173
	v_sub_f32_e32 v50, v64, v50
	v_mul_f32_e32 v64, 0xbfb8aa3b, v52
	v_exp_f32_e32 v64, v64
	v_mul_f32_e32 v50, v50, v66
	v_mul_f32_e32 v50, v148, v50
	v_add_f32_e32 v64, 1.0, v64
	v_rcp_f32_e32 v64, v64
	s_nop 0
	v_mul_f32_e32 v52, v52, v64
	v_mul_f32_e32 v50, v52, v50
	global_load_dwordx4 v[66:69], v[70:71], off offset:16
	s_nop 0
	global_load_dwordx4 v[70:73], v[70:71], off
	s_nop 0
	v_cvt_pk_bf16_f32 v50, v50, s0
	global_store_short v[76:77], v0, off
	global_store_short v[76:77], v58, off offset:32
	global_store_short v[76:77], v54, off offset:256
	global_store_short v[76:77], v62, off offset:288
	global_store_short v[78:79], v63, off
	global_store_short v[78:79], v59, off offset:32
	global_store_short v[78:79], v55, off offset:256
	global_store_short v[78:79], v82, off offset:288
	global_store_short v[80:81], v51, off
	global_store_short v[80:81], v60, off offset:32
	global_store_short v[80:81], v56, off offset:256
	global_store_short v[80:81], v50, off offset:288
	v_add_u32_e32 v54, 0x90, v152
	s_waitcnt vmcnt(0)
	v_pk_add_f32 v[50:51], v[70:71], v[72:73]
	s_nop 0
	v_pk_add_f32 v[50:51], v[50:51], v[66:67]
	s_nop 0
	v_pk_add_f32 v[50:51], v[50:51], v[68:69]
	s_nop 0
	v_pk_mul_f32 v[50:51], v[50:51], s[18:19] op_sel_hi:[1,0]
	s_nop 0
	v_fma_f32 v0, -v50, v50, v51
	v_max_f32_e32 v0, 0, v0
	v_add_f32_e32 v0, 0x3727c5ac, v0
	v_cmp_gt_f32_e32 vcc, s25, v0
	v_mul_f32_e32 v51, 0x4b800000, v0
	s_nop 0
	v_cndmask_b32_e32 v0, v0, v51, vcc
	v_rsq_f32_e32 v0, v0
	s_nop 0
	v_mul_f32_e32 v51, 0x45800000, v0
	v_cndmask_b32_e32 v0, v0, v51, vcc
	s_waitcnt vmcnt(0)
	v_lshlrev_b32_e32 v51, 16, v174
	v_mul_f32_e32 v52, 0xbfb8aa3b, v65
	v_exp_f32_e32 v52, v52
	v_sub_f32_e32 v51, v51, v50
	v_mul_f32_e32 v51, v51, v0
	v_mul_f32_e32 v51, v151, v51
	v_add_f32_e32 v52, 1.0, v52
	v_rcp_f32_e32 v52, v52
	s_nop 0
	v_mul_f32_e32 v52, v65, v52
	v_mul_f32_e32 v51, v52, v51
	v_mul_f32_e32 v52, 0xbfb8aa3b, v61
	v_exp_f32_e32 v52, v52
	v_cvt_pk_bf16_f32 v51, v51, s0
	global_store_short v[74:75], v51, off
	s_waitcnt vmcnt(0)
	v_lshlrev_b32_e32 v51, 16, v175
	v_add_f32_e32 v52, 1.0, v52
	v_rcp_f32_e32 v52, v52
	v_sub_f32_e32 v51, v51, v50
	v_mul_f32_e32 v51, v51, v0
	v_mul_f32_e32 v51, v150, v51
	v_mul_f32_e32 v52, v61, v52
	v_mul_f32_e32 v51, v52, v51
	v_mul_f32_e32 v52, 0xbfb8aa3b, v57
	v_exp_f32_e32 v52, v52
	v_cvt_pk_bf16_f32 v51, v51, s0
	global_store_short v[74:75], v51, off offset:32
	s_waitcnt vmcnt(0)
	v_lshlrev_b32_e32 v51, 16, v176
	v_add_f32_e32 v52, 1.0, v52
	v_rcp_f32_e32 v52, v52
	v_sub_f32_e32 v51, v51, v50
	v_mul_f32_e32 v51, v51, v0
	v_mul_f32_e32 v51, v149, v51
	v_mul_f32_e32 v52, v57, v52
	v_mul_f32_e32 v51, v52, v51
	v_cvt_pk_bf16_f32 v51, v51, s0
	global_store_short v[74:75], v51, off offset:256
	s_waitcnt vmcnt(0)
; __device__ __forceinline__ float bf2f(u16 b) { return __uint_as_float(((unsigned)b) << 16); }
; __device__ __forceinline__ float silu_f(float g) { return g * __builtin_amdgcn_rcpf(1.f + __builtin_amdgcn_exp2f(-g * LOG2E)); }
; template <int EPI>
; __device__ __forceinline__ void epilogue(const Params& p, int pass, int layer, int pm, int pn,
;                                          f32x4 (&acc)[2][2][4][2], const float* xin, float* xout) {
;     ...
;       for (int m = 0; m < 4; ++m) {
;         int tb = t0 + ai * 128 + wr * 64 + m * 16 + fq * 4;
;         asm volatile("" : "+v"(tb));
;         float4 s01[4], s23[4];
;         u16 yv[4][2][2];
; #pragma unroll
;         for (int j = 0; j < 4; ++j) {
;           const float4* sp = (const float4*)(stat + ((long)(tb + j) * 8 + h) * 8);
;           s01[j] = sp[0]; s23[j] = sp[1];
; #pragma unroll
;           for (int bj = 0; bj < 2; ++bj)
; #pragma unroll
;             for (int n = 0; n < 2; ++n)
;               yv[j][bj][n] = Y[(long)(tb + j) * YS + pn * 256 + bj * 128 + wc * 32 + n * 16 + fr];
;         }
; #pragma unroll
;         for (int j = 0; j < 4; ++j) {
;           float s1 = s01[j].x + s01[j].z + s23[j].x + s23[j].z, s2 = s01[j].y + s01[j].w + s23[j].y + s23[j].w;
;           float mu = s1 * (1.f / 512.f);
;           float var = s2 * (1.f / 512.f) - mu * mu;
;           float rstd = rsqrtf(fmaxf(var, 0.f) + 1e-5f);
; #pragma unroll
;           for (int bj = 0; bj < 2; ++bj)
; #pragma unroll
;             for (int n = 0; n < 2; ++n) {
;               float g = acc[ai][bj][m][n][j];
;               float yn = (bf2f(yv[j][bj][n]) - mu) * rstd * gn[bj][n];
;               Y[(long)(tb + j) * YS + pn * 256 + bj * 128 + wc * 32 + n * 16 + fr] = f2bf(silu_f(g) * yn);
;             }
;         }
	v_lshlrev_b32_e32 v51, 16, v177
	v_sub_f32_e32 v50, v51, v50
	v_mul_f32_e32 v0, v50, v0
	v_mul_f32_e32 v50, 0xbfb8aa3b, v53
	v_exp_f32_e32 v50, v50
	v_mul_f32_e32 v0, v148, v0
	v_add_f32_e32 v50, 1.0, v50
	v_rcp_f32_e32 v50, v50
	s_nop 0
	v_mul_f32_e32 v50, v53, v50
	v_mul_f32_e32 v0, v50, v0
	v_cvt_pk_bf16_f32 v0, v0, s0
	global_store_short v[74:75], v0, off offset:288
	s_nop 0
	v_ashrrev_i32_e32 v55, 31, v54
	v_lshlrev_b64 v[50:51], 8, v[54:55]
	v_lshl_add_u64 v[56:57], s[16:17], 0, v[50:51]
	global_load_dwordx4 v[66:69], v[56:57], off offset:16
	global_load_dwordx4 v[70:73], v[56:57], off
	v_mad_i64_i32 v[60:61], s[14:15], v54, s24, v[138:139]
	global_load_ushort v178, v[60:61], off
	global_load_ushort v179, v[60:61], off offset:32
	global_load_ushort v180, v[60:61], off offset:256
	global_load_ushort v181, v[60:61], off offset:288
	v_add_u32_e32 v50, 1, v54
	v_ashrrev_i32_e32 v51, 31, v50
	v_lshlrev_b64 v[52:53], 8, v[50:51]
	v_lshl_add_u64 v[52:53], s[16:17], 0, v[52:53]
	v_mad_i64_i32 v[62:63], s[14:15], v50, s24, v[138:139]
	global_load_ushort v182, v[62:63], off
	global_load_ushort v183, v[62:63], off offset:32
	global_load_ushort v184, v[62:63], off offset:256
	global_load_ushort v185, v[62:63], off offset:288
	v_add_u32_e32 v58, 2, v54
	v_ashrrev_i32_e32 v59, 31, v58
	v_lshlrev_b64 v[50:51], 8, v[58:59]
	v_lshl_add_u64 v[50:51], s[16:17], 0, v[50:51]
	v_mad_i64_i32 v[64:65], s[14:15], v58, s24, v[138:139]
	global_load_ushort v186, v[64:65], off
	global_load_ushort v187, v[64:65], off offset:32
	global_load_ushort v188, v[64:65], off offset:256
	global_load_ushort v189, v[64:65], off offset:288
	v_add_u32_e32 v58, 3, v54
	v_ashrrev_i32_e32 v59, 31, v58
	v_lshlrev_b64 v[54:55], 8, v[58:59]
	v_lshl_add_u64 v[54:55], s[16:17], 0, v[54:55]
	v_mad_i64_i32 v[58:59], s[14:15], v58, s24, v[138:139]
	global_load_ushort v190, v[58:59], off
	global_load_ushort v191, v[58:59], off offset:32
	global_load_ushort v192, v[58:59], off offset:256
	global_load_ushort v193, v[58:59], off offset:288
	s_waitcnt vmcnt(0)
	v_pk_add_f32 v[56:57], v[70:71], v[72:73]
	s_nop 0
	v_pk_add_f32 v[56:57], v[56:57], v[66:67]
	v_mul_f32_e32 v66, 0xbfb8aa3b, v46
	v_pk_add_f32 v[56:57], v[56:57], v[68:69]
	v_exp_f32_e32 v66, v66
	v_pk_mul_f32 v[56:57], v[56:57], s[18:19] op_sel_hi:[1,0]
	v_add_f32_e32 v66, 1.0, v66
	v_fma_f32 v0, -v56, v56, v57
	v_max_f32_e32 v0, 0, v0
	v_add_f32_e32 v0, 0x3727c5ac, v0
	v_cmp_gt_f32_e32 vcc, s25, v0
	v_mul_f32_e32 v57, 0x4b800000, v0
	v_rcp_f32_e32 v66, v66
	v_cndmask_b32_e32 v0, v0, v57, vcc
	v_rsq_f32_e32 v0, v0
	v_mul_f32_e32 v46, v46, v66
	v_mul_f32_e32 v66, 0xbfb8aa3b, v42
	v_mul_f32_e32 v57, 0x45800000, v0
	v_cndmask_b32_e32 v57, v0, v57, vcc
	v_exp_f32_e32 v66, v66
	s_waitcnt vmcnt(0)
	v_lshlrev_b32_e32 v0, 16, v178
	v_sub_f32_e32 v0, v0, v56
	v_mul_f32_e32 v0, v0, v57
	v_mul_f32_e32 v0, v151, v0
	v_mul_f32_e32 v0, v46, v0
	v_add_f32_e32 v66, 1.0, v66
	v_rcp_f32_e32 v66, v66
	v_cvt_pk_bf16_f32 v0, v0, s0
	v_mul_f32_e32 v42, v42, v66
	v_mul_f32_e32 v66, 0xbfb8aa3b, v38
	v_exp_f32_e32 v66, v66
	s_waitcnt vmcnt(0)
	v_lshlrev_b32_e32 v46, 16, v179
	v_sub_f32_e32 v46, v46, v56
	v_mul_f32_e32 v46, v46, v57
	v_mul_f32_e32 v46, v150, v46
	v_mul_f32_e32 v42, v42, v46
	v_add_f32_e32 v66, 1.0, v66
	v_rcp_f32_e32 v66, v66
	v_cvt_pk_bf16_f32 v42, v42, s0
	v_mul_f32_e32 v38, v38, v66
	s_waitcnt vmcnt(0)
	v_lshlrev_b32_e32 v46, 16, v180
	v_sub_f32_e32 v46, v46, v56
	v_mul_f32_e32 v46, v46, v57
	v_mul_f32_e32 v46, v149, v46
	v_mul_f32_e32 v38, v38, v46
	global_load_dwordx4 v[66:69], v[52:53], off offset:16
	global_load_dwordx4 v[70:73], v[52:53], off
	v_cvt_pk_bf16_f32 v38, v38, s0
	s_waitcnt vmcnt(0)
	v_lshlrev_b32_e32 v46, 16, v181
	v_sub_f32_e32 v46, v46, v56
	v_mul_f32_e32 v56, 0xbfb8aa3b, v34
	v_exp_f32_e32 v56, v56
	s_waitcnt vmcnt(0)
	v_pk_add_f32 v[52:53], v[70:71], v[72:73]
	v_mul_f32_e32 v46, v46, v57
	v_pk_add_f32 v[52:53], v[52:53], v[66:67]
	v_add_f32_e32 v56, 1.0, v56
	v_rcp_f32_e32 v56, v56
	v_mul_f32_e32 v46, v148, v46
	v_pk_add_f32 v[52:53], v[52:53], v[68:69]
	v_mul_f32_e32 v34, v34, v56
	v_mul_f32_e32 v34, v34, v46
	v_pk_mul_f32 v[52:53], v[52:53], s[18:19] op_sel_hi:[1,0]
	v_cvt_pk_bf16_f32 v46, v34, s0
	v_fma_f32 v34, -v52, v52, v53
	v_max_f32_e32 v34, 0, v34
	v_add_f32_e32 v34, 0x3727c5ac, v34
	v_cmp_gt_f32_e32 vcc, s25, v34
	v_mul_f32_e32 v53, 0x4b800000, v34
	v_mul_f32_e32 v56, 0xbfb8aa3b, v47
	v_cndmask_b32_e32 v34, v34, v53, vcc
	v_rsq_f32_e32 v34, v34
	v_exp_f32_e32 v56, v56
	v_mul_f32_e32 v53, 0x45800000, v34
	v_cndmask_b32_e32 v34, v34, v53, vcc
	v_add_f32_e32 v56, 1.0, v56
	v_rcp_f32_e32 v56, v56
	s_waitcnt vmcnt(0)
	v_lshlrev_b32_e32 v53, 16, v182
	v_sub_f32_e32 v53, v53, v52
	v_mul_f32_e32 v53, v53, v34
	v_mul_f32_e32 v53, v151, v53
	v_mul_f32_e32 v47, v47, v56
	v_mul_f32_e32 v47, v47, v53
	v_mul_f32_e32 v56, 0xbfb8aa3b, v43
	v_exp_f32_e32 v56, v56
	v_cvt_pk_bf16_f32 v47, v47, s0
	v_add_f32_e32 v56, 1.0, v56
	v_rcp_f32_e32 v56, v56
	s_waitcnt vmcnt(0)
	v_lshlrev_b32_e32 v53, 16, v183
	v_sub_f32_e32 v53, v53, v52
	v_mul_f32_e32 v53, v53, v34
	v_mul_f32_e32 v53, v150, v53
	v_mul_f32_e32 v43, v43, v56
	v_mul_f32_e32 v43, v43, v53
	v_mul_f32_e32 v56, 0xbfb8aa3b, v39
	v_exp_f32_e32 v56, v56
	v_cvt_pk_bf16_f32 v43, v43, s0
	v_add_f32_e32 v56, 1.0, v56
	v_rcp_f32_e32 v56, v56
	s_waitcnt vmcnt(0)
	v_lshlrev_b32_e32 v53, 16, v184
	v_sub_f32_e32 v53, v53, v52
	v_mul_f32_e32 v53, v53, v34
	v_mul_f32_e32 v53, v149, v53
	v_mul_f32_e32 v39, v39, v56
	v_mul_f32_e32 v39, v39, v53
	v_cvt_pk_bf16_f32 v39, v39, s0
	s_waitcnt vmcnt(0)
; __device__ __forceinline__ float bf2f(u16 b) { return __uint_as_float(((unsigned)b) << 16); }
; __device__ __forceinline__ float silu_f(float g) { return g * __builtin_amdgcn_rcpf(1.f + __builtin_amdgcn_exp2f(-g * LOG2E)); }
; template <int EPI>
; __device__ __forceinline__ void epilogue(const Params& p, int pass, int layer, int pm, int pn,
;                                          f32x4 (&acc)[2][2][4][2], const float* xin, float* xout) {
;     ...
;       for (int m = 0; m < 4; ++m) {
;         int tb = t0 + ai * 128 + wr * 64 + m * 16 + fq * 4;
;         asm volatile("" : "+v"(tb));
;         float4 s01[4], s23[4];
;         u16 yv[4][2][2];
; #pragma unroll
;         for (int j = 0; j < 4; ++j) {
;           const float4* sp = (const float4*)(stat + ((long)(tb + j) * 8 + h) * 8);
;           s01[j] = sp[0]; s23[j] = sp[1];
; #pragma unroll
;           for (int bj = 0; bj < 2; ++bj)
; #pragma unroll
;             for (int n = 0; n < 2; ++n)
;               yv[j][bj][n] = Y[(long)(tb + j) * YS + pn * 256 + bj * 128 + wc * 32 + n * 16 + fr];
;         }
; #pragma unroll
;         for (int j = 0; j < 4; ++j) {
;           float s1 = s01[j].x + s01[j].z + s23[j].x + s23[j].z, s2 = s01[j].y + s01[j].w + s23[j].y + s23[j].w;
;           float mu = s1 * (1.f / 512.f);
;           float var = s2 * (1.f / 512.f) - mu * mu;
;           float rstd = rsqrtf(fmaxf(var, 0.f) + 1e-5f);
; #pragma unroll
;           for (int bj = 0; bj < 2; ++bj)
; #pragma unroll
;             for (int n = 0; n < 2; ++n) {
;               float g = acc[ai][bj][m][n][j];
;               float yn = (bf2f(yv[j][bj][n]) - mu) * rstd * gn[bj][n];
;               Y[(long)(tb + j) * YS + pn * 256 + bj * 128 + wc * 32 + n * 16 + fr] = f2bf(silu_f(g) * yn);
;             }
;         }
	v_lshlrev_b32_e32 v53, 16, v185
	v_sub_f32_e32 v52, v53, v52
	v_mul_f32_e32 v34, v52, v34
	v_mul_f32_e32 v52, 0xbfb8aa3b, v35
	v_exp_f32_e32 v52, v52
	v_mul_f32_e32 v34, v148, v34
	v_add_f32_e32 v52, 1.0, v52
	v_rcp_f32_e32 v52, v52
	s_nop 0
	v_mul_f32_e32 v35, v35, v52
	global_load_dwordx4 v[68:71], v[50:51], off offset:16
	s_nop 0
	global_load_dwordx4 v[50:53], v[50:51], off
	v_mul_f32_e32 v34, v35, v34
	v_cvt_pk_bf16_f32 v66, v34, s0
	s_waitcnt vmcnt(0)
	v_pk_add_f32 v[34:35], v[50:51], v[52:53]
	s_nop 0
	v_pk_add_f32 v[34:35], v[34:35], v[68:69]
	v_mul_f32_e32 v51, 0xbfb8aa3b, v48
	v_pk_add_f32 v[34:35], v[34:35], v[70:71]
	v_exp_f32_e32 v51, v51
	v_pk_mul_f32 v[34:35], v[34:35], s[18:19] op_sel_hi:[1,0]
	v_add_f32_e32 v51, 1.0, v51
	v_fma_f32 v35, -v34, v34, v35
	v_max_f32_e32 v35, 0, v35
	v_add_f32_e32 v35, 0x3727c5ac, v35
	v_cmp_gt_f32_e32 vcc, s25, v35
	v_mul_f32_e32 v50, 0x4b800000, v35
	v_rcp_f32_e32 v51, v51
	v_cndmask_b32_e32 v35, v35, v50, vcc
	v_rsq_f32_e32 v35, v35
	v_mul_f32_e32 v48, v48, v51
	v_mul_f32_e32 v51, 0xbfb8aa3b, v44
	v_mul_f32_e32 v50, 0x45800000, v35
	v_cndmask_b32_e32 v50, v35, v50, vcc
	v_exp_f32_e32 v51, v51
	s_waitcnt vmcnt(0)
	v_lshlrev_b32_e32 v35, 16, v186
	v_sub_f32_e32 v35, v35, v34
	v_mul_f32_e32 v35, v35, v50
	v_mul_f32_e32 v35, v151, v35
	v_mul_f32_e32 v35, v48, v35
	v_add_f32_e32 v51, 1.0, v51
	v_rcp_f32_e32 v51, v51
	v_cvt_pk_bf16_f32 v35, v35, s0
	v_mul_f32_e32 v44, v44, v51
	v_mul_f32_e32 v51, 0xbfb8aa3b, v40
	v_exp_f32_e32 v51, v51
	s_waitcnt vmcnt(0)
	v_lshlrev_b32_e32 v48, 16, v187
	v_sub_f32_e32 v48, v48, v34
	v_mul_f32_e32 v48, v48, v50
	v_mul_f32_e32 v48, v150, v48
	v_mul_f32_e32 v44, v44, v48
	v_add_f32_e32 v51, 1.0, v51
	v_rcp_f32_e32 v51, v51
	v_cvt_pk_bf16_f32 v44, v44, s0
	v_mul_f32_e32 v40, v40, v51
	s_waitcnt vmcnt(0)
	v_lshlrev_b32_e32 v48, 16, v188
	v_sub_f32_e32 v48, v48, v34
	v_mul_f32_e32 v48, v48, v50
	v_mul_f32_e32 v48, v149, v48
	v_mul_f32_e32 v40, v40, v48
	v_cvt_pk_bf16_f32 v40, v40, s0
	s_waitcnt vmcnt(0)
	v_lshlrev_b32_e32 v48, 16, v189
	v_sub_f32_e32 v34, v48, v34
	v_mul_f32_e32 v48, 0xbfb8aa3b, v36
	v_exp_f32_e32 v48, v48
	v_mul_f32_e32 v34, v34, v50
	v_mul_f32_e32 v34, v148, v34
	v_add_f32_e32 v48, 1.0, v48
	v_rcp_f32_e32 v48, v48
	s_nop 0
	v_mul_f32_e32 v36, v36, v48
	v_mul_f32_e32 v34, v36, v34
	global_load_dwordx4 v[50:53], v[54:55], off offset:16
	s_nop 0
	global_load_dwordx4 v[54:57], v[54:55], off
	s_nop 0
	v_cvt_pk_bf16_f32 v34, v34, s0
	global_store_short v[60:61], v0, off
	global_store_short v[60:61], v42, off offset:32
	global_store_short v[60:61], v38, off offset:256
	global_store_short v[60:61], v46, off offset:288
	global_store_short v[62:63], v47, off
	global_store_short v[62:63], v43, off offset:32
	global_store_short v[62:63], v39, off offset:256
	global_store_short v[62:63], v66, off offset:288
	global_store_short v[64:65], v35, off
	global_store_short v[64:65], v44, off offset:32
	global_store_short v[64:65], v40, off offset:256
	global_store_short v[64:65], v34, off offset:288
	v_add_u32_e32 v38, 0xa0, v152
	s_waitcnt vmcnt(0)
	v_pk_add_f32 v[34:35], v[54:55], v[56:57]
	s_nop 0
	v_pk_add_f32 v[34:35], v[34:35], v[50:51]
	s_nop 0
	v_pk_add_f32 v[34:35], v[34:35], v[52:53]
	s_nop 0
	v_pk_mul_f32 v[34:35], v[34:35], s[18:19] op_sel_hi:[1,0]
	s_nop 0
	v_fma_f32 v0, -v34, v34, v35
	v_max_f32_e32 v0, 0, v0
	v_add_f32_e32 v0, 0x3727c5ac, v0
	v_cmp_gt_f32_e32 vcc, s25, v0
	v_mul_f32_e32 v35, 0x4b800000, v0
	s_nop 0
	v_cndmask_b32_e32 v0, v0, v35, vcc
	v_rsq_f32_e32 v0, v0
	s_nop 0
	v_mul_f32_e32 v35, 0x45800000, v0
	v_cndmask_b32_e32 v0, v0, v35, vcc
	s_waitcnt vmcnt(0)
	v_lshlrev_b32_e32 v35, 16, v190
	v_mul_f32_e32 v36, 0xbfb8aa3b, v49
	v_exp_f32_e32 v36, v36
	v_sub_f32_e32 v35, v35, v34
	v_mul_f32_e32 v35, v35, v0
	v_mul_f32_e32 v35, v151, v35
	v_add_f32_e32 v36, 1.0, v36
	v_rcp_f32_e32 v36, v36
	s_nop 0
	v_mul_f32_e32 v36, v49, v36
	v_mul_f32_e32 v35, v36, v35
	v_mul_f32_e32 v36, 0xbfb8aa3b, v45
	v_exp_f32_e32 v36, v36
	v_cvt_pk_bf16_f32 v35, v35, s0
	global_store_short v[58:59], v35, off
	s_waitcnt vmcnt(0)
	v_lshlrev_b32_e32 v35, 16, v191
	v_add_f32_e32 v36, 1.0, v36
	v_rcp_f32_e32 v36, v36
	v_sub_f32_e32 v35, v35, v34
	v_mul_f32_e32 v35, v35, v0
	v_mul_f32_e32 v35, v150, v35
	v_mul_f32_e32 v36, v45, v36
	v_mul_f32_e32 v35, v36, v35
	v_mul_f32_e32 v36, 0xbfb8aa3b, v41
	v_exp_f32_e32 v36, v36
	v_cvt_pk_bf16_f32 v35, v35, s0
	global_store_short v[58:59], v35, off offset:32
	s_waitcnt vmcnt(0)
	v_lshlrev_b32_e32 v35, 16, v192
	v_add_f32_e32 v36, 1.0, v36
	v_rcp_f32_e32 v36, v36
	v_sub_f32_e32 v35, v35, v34
	v_mul_f32_e32 v35, v35, v0
	v_mul_f32_e32 v35, v149, v35
	v_mul_f32_e32 v36, v41, v36
	v_mul_f32_e32 v35, v36, v35
	v_cvt_pk_bf16_f32 v35, v35, s0
	global_store_short v[58:59], v35, off offset:256
	s_waitcnt vmcnt(0)
; __device__ __forceinline__ float bf2f(u16 b) { return __uint_as_float(((unsigned)b) << 16); }
; __device__ __forceinline__ float silu_f(float g) { return g * __builtin_amdgcn_rcpf(1.f + __builtin_amdgcn_exp2f(-g * LOG2E)); }
; template <int EPI>
; __device__ __forceinline__ void epilogue(const Params& p, int pass, int layer, int pm, int pn,
;                                          f32x4 (&acc)[2][2][4][2], const float* xin, float* xout) {
;     ...
;       for (int m = 0; m < 4; ++m) {
;         int tb = t0 + ai * 128 + wr * 64 + m * 16 + fq * 4;
;         asm volatile("" : "+v"(tb));
;         float4 s01[4], s23[4];
;         u16 yv[4][2][2];
; #pragma unroll
;         for (int j = 0; j < 4; ++j) {
;           const float4* sp = (const float4*)(stat + ((long)(tb + j) * 8 + h) * 8);
;           s01[j] = sp[0]; s23[j] = sp[1];
; #pragma unroll
;           for (int bj = 0; bj < 2; ++bj)
; #pragma unroll
;             for (int n = 0; n < 2; ++n)
;               yv[j][bj][n] = Y[(long)(tb + j) * YS + pn * 256 + bj * 128 + wc * 32 + n * 16 + fr];
;         }
; #pragma unroll
;         for (int j = 0; j < 4; ++j) {
;           float s1 = s01[j].x + s01[j].z + s23[j].x + s23[j].z, s2 = s01[j].y + s01[j].w + s23[j].y + s23[j].w;
;           float mu = s1 * (1.f / 512.f);
;           float var = s2 * (1.f / 512.f) - mu * mu;
;           float rstd = rsqrtf(fmaxf(var, 0.f) + 1e-5f);
; #pragma unroll
;           for (int bj = 0; bj < 2; ++bj)
; #pragma unroll
;             for (int n = 0; n < 2; ++n) {
;               float g = acc[ai][bj][m][n][j];
;               float yn = (bf2f(yv[j][bj][n]) - mu) * rstd * gn[bj][n];
;               Y[(long)(tb + j) * YS + pn * 256 + bj * 128 + wc * 32 + n * 16 + fr] = f2bf(silu_f(g) * yn);
;             }
;         }
	v_lshlrev_b32_e32 v35, 16, v193
	v_sub_f32_e32 v34, v35, v34
	v_mul_f32_e32 v0, v34, v0
	v_mul_f32_e32 v34, 0xbfb8aa3b, v37
	v_exp_f32_e32 v34, v34
	v_mul_f32_e32 v0, v148, v0
	v_add_f32_e32 v34, 1.0, v34
	v_rcp_f32_e32 v34, v34
	s_nop 0
	v_mul_f32_e32 v34, v37, v34
	v_mul_f32_e32 v0, v34, v0
	v_cvt_pk_bf16_f32 v0, v0, s0
	global_store_short v[58:59], v0, off offset:288
	s_nop 0
	v_ashrrev_i32_e32 v39, 31, v38
	v_lshlrev_b64 v[34:35], 8, v[38:39]
	v_lshl_add_u64 v[40:41], s[16:17], 0, v[34:35]
	global_load_dwordx4 v[50:53], v[40:41], off offset:16
	global_load_dwordx4 v[54:57], v[40:41], off
	v_mad_i64_i32 v[44:45], s[14:15], v38, s24, v[138:139]
	global_load_ushort v162, v[44:45], off
	global_load_ushort v163, v[44:45], off offset:32
	global_load_ushort v164, v[44:45], off offset:256
	global_load_ushort v165, v[44:45], off offset:288
	v_add_u32_e32 v34, 1, v38
	v_ashrrev_i32_e32 v35, 31, v34
	v_lshlrev_b64 v[36:37], 8, v[34:35]
	v_lshl_add_u64 v[36:37], s[16:17], 0, v[36:37]
	v_mad_i64_i32 v[46:47], s[14:15], v34, s24, v[138:139]
	global_load_ushort v166, v[46:47], off
	global_load_ushort v167, v[46:47], off offset:32
	global_load_ushort v168, v[46:47], off offset:256
	global_load_ushort v169, v[46:47], off offset:288
	v_add_u32_e32 v42, 2, v38
	v_ashrrev_i32_e32 v43, 31, v42
	v_lshlrev_b64 v[34:35], 8, v[42:43]
	v_lshl_add_u64 v[34:35], s[16:17], 0, v[34:35]
	v_mad_i64_i32 v[48:49], s[14:15], v42, s24, v[138:139]
	global_load_ushort v170, v[48:49], off
	global_load_ushort v171, v[48:49], off offset:32
	global_load_ushort v172, v[48:49], off offset:256
	global_load_ushort v173, v[48:49], off offset:288
	v_add_u32_e32 v42, 3, v38
	v_ashrrev_i32_e32 v43, 31, v42
	v_lshlrev_b64 v[38:39], 8, v[42:43]
	v_lshl_add_u64 v[38:39], s[16:17], 0, v[38:39]
	v_mad_i64_i32 v[42:43], s[14:15], v42, s24, v[138:139]
	global_load_ushort v174, v[42:43], off
	global_load_ushort v175, v[42:43], off offset:32
	global_load_ushort v176, v[42:43], off offset:256
	global_load_ushort v177, v[42:43], off offset:288
	s_waitcnt vmcnt(0)
	v_pk_add_f32 v[40:41], v[54:55], v[56:57]
	s_nop 0
	v_pk_add_f32 v[40:41], v[40:41], v[50:51]
	v_mul_f32_e32 v50, 0xbfb8aa3b, v30
	v_pk_add_f32 v[40:41], v[40:41], v[52:53]
	v_exp_f32_e32 v50, v50
	v_pk_mul_f32 v[40:41], v[40:41], s[18:19] op_sel_hi:[1,0]
	v_add_f32_e32 v50, 1.0, v50
	v_fma_f32 v0, -v40, v40, v41
	v_max_f32_e32 v0, 0, v0
	v_add_f32_e32 v0, 0x3727c5ac, v0
	v_cmp_gt_f32_e32 vcc, s25, v0
	v_mul_f32_e32 v41, 0x4b800000, v0
	v_rcp_f32_e32 v50, v50
	v_cndmask_b32_e32 v0, v0, v41, vcc
	v_rsq_f32_e32 v0, v0
	v_mul_f32_e32 v30, v30, v50
	v_mul_f32_e32 v50, 0xbfb8aa3b, v26
	v_mul_f32_e32 v41, 0x45800000, v0
	v_cndmask_b32_e32 v41, v0, v41, vcc
	v_exp_f32_e32 v50, v50
	s_waitcnt vmcnt(0)
	v_lshlrev_b32_e32 v0, 16, v162
	v_sub_f32_e32 v0, v0, v40
	v_mul_f32_e32 v0, v0, v41
	v_mul_f32_e32 v0, v151, v0
	v_mul_f32_e32 v0, v30, v0
	v_add_f32_e32 v50, 1.0, v50
	v_rcp_f32_e32 v50, v50
	v_cvt_pk_bf16_f32 v0, v0, s0
	v_mul_f32_e32 v26, v26, v50
	v_mul_f32_e32 v50, 0xbfb8aa3b, v22
	v_exp_f32_e32 v50, v50
	s_waitcnt vmcnt(0)
	v_lshlrev_b32_e32 v30, 16, v163
	v_sub_f32_e32 v30, v30, v40
	v_mul_f32_e32 v30, v30, v41
	v_mul_f32_e32 v30, v150, v30
	v_mul_f32_e32 v26, v26, v30
	v_add_f32_e32 v50, 1.0, v50
	v_rcp_f32_e32 v50, v50
	v_cvt_pk_bf16_f32 v26, v26, s0
	v_mul_f32_e32 v22, v22, v50
	s_waitcnt vmcnt(0)
	v_lshlrev_b32_e32 v30, 16, v164
	v_sub_f32_e32 v30, v30, v40
	v_mul_f32_e32 v30, v30, v41
	v_mul_f32_e32 v30, v149, v30
	v_mul_f32_e32 v22, v22, v30
	global_load_dwordx4 v[50:53], v[36:37], off offset:16
	global_load_dwordx4 v[54:57], v[36:37], off
	v_cvt_pk_bf16_f32 v22, v22, s0
	s_waitcnt vmcnt(0)
	v_lshlrev_b32_e32 v30, 16, v165
	v_sub_f32_e32 v30, v30, v40
	v_mul_f32_e32 v40, 0xbfb8aa3b, v18
	v_exp_f32_e32 v40, v40
	s_waitcnt vmcnt(0)
	v_pk_add_f32 v[36:37], v[54:55], v[56:57]
	v_mul_f32_e32 v30, v30, v41
	v_pk_add_f32 v[36:37], v[36:37], v[50:51]
	v_add_f32_e32 v40, 1.0, v40
	v_rcp_f32_e32 v40, v40
	v_mul_f32_e32 v30, v148, v30
	v_pk_add_f32 v[36:37], v[36:37], v[52:53]
	v_mul_f32_e32 v18, v18, v40
	v_mul_f32_e32 v18, v18, v30
	v_pk_mul_f32 v[36:37], v[36:37], s[18:19] op_sel_hi:[1,0]
	v_cvt_pk_bf16_f32 v30, v18, s0
	v_fma_f32 v18, -v36, v36, v37
	v_max_f32_e32 v18, 0, v18
	v_add_f32_e32 v18, 0x3727c5ac, v18
	v_cmp_gt_f32_e32 vcc, s25, v18
	v_mul_f32_e32 v37, 0x4b800000, v18
	v_mul_f32_e32 v40, 0xbfb8aa3b, v31
	v_cndmask_b32_e32 v18, v18, v37, vcc
	v_rsq_f32_e32 v18, v18
	v_exp_f32_e32 v40, v40
	v_mul_f32_e32 v37, 0x45800000, v18
	v_cndmask_b32_e32 v18, v18, v37, vcc
	v_add_f32_e32 v40, 1.0, v40
	v_rcp_f32_e32 v40, v40
	s_waitcnt vmcnt(0)
	v_lshlrev_b32_e32 v37, 16, v166
	v_sub_f32_e32 v37, v37, v36
	v_mul_f32_e32 v37, v37, v18
	v_mul_f32_e32 v37, v151, v37
	v_mul_f32_e32 v31, v31, v40
	v_mul_f32_e32 v31, v31, v37
	v_mul_f32_e32 v40, 0xbfb8aa3b, v27
	v_exp_f32_e32 v40, v40
	v_cvt_pk_bf16_f32 v31, v31, s0
	v_add_f32_e32 v40, 1.0, v40
	v_rcp_f32_e32 v40, v40
	s_waitcnt vmcnt(0)
	v_lshlrev_b32_e32 v37, 16, v167
	v_sub_f32_e32 v37, v37, v36
	v_mul_f32_e32 v37, v37, v18
	v_mul_f32_e32 v37, v150, v37
	v_mul_f32_e32 v27, v27, v40
	v_mul_f32_e32 v27, v27, v37
	v_mul_f32_e32 v40, 0xbfb8aa3b, v23
	v_exp_f32_e32 v40, v40
	v_cvt_pk_bf16_f32 v27, v27, s0
	v_add_f32_e32 v40, 1.0, v40
	v_rcp_f32_e32 v40, v40
	s_waitcnt vmcnt(0)
	v_lshlrev_b32_e32 v37, 16, v168
	v_sub_f32_e32 v37, v37, v36
	v_mul_f32_e32 v37, v37, v18
	v_mul_f32_e32 v37, v149, v37
	v_mul_f32_e32 v23, v23, v40
	v_mul_f32_e32 v23, v23, v37
	v_cvt_pk_bf16_f32 v23, v23, s0
	s_waitcnt vmcnt(0)
; __device__ __forceinline__ float bf2f(u16 b) { return __uint_as_float(((unsigned)b) << 16); }
; __device__ __forceinline__ float silu_f(float g) { return g * __builtin_amdgcn_rcpf(1.f + __builtin_amdgcn_exp2f(-g * LOG2E)); }
; template <int EPI>
; __device__ __forceinline__ void epilogue(const Params& p, int pass, int layer, int pm, int pn,
;                                          f32x4 (&acc)[2][2][4][2], const float* xin, float* xout) {
;     ...
;       for (int m = 0; m < 4; ++m) {
;         int tb = t0 + ai * 128 + wr * 64 + m * 16 + fq * 4;
;         asm volatile("" : "+v"(tb));
;         float4 s01[4], s23[4];
;         u16 yv[4][2][2];
; #pragma unroll
;         for (int j = 0; j < 4; ++j) {
;           const float4* sp = (const float4*)(stat + ((long)(tb + j) * 8 + h) * 8);
;           s01[j] = sp[0]; s23[j] = sp[1];
; #pragma unroll
;           for (int bj = 0; bj < 2; ++bj)
; #pragma unroll
;             for (int n = 0; n < 2; ++n)
;               yv[j][bj][n] = Y[(long)(tb + j) * YS + pn * 256 + bj * 128 + wc * 32 + n * 16 + fr];
;         }
; #pragma unroll
;         for (int j = 0; j < 4; ++j) {
;           float s1 = s01[j].x + s01[j].z + s23[j].x + s23[j].z, s2 = s01[j].y + s01[j].w + s23[j].y + s23[j].w;
;           float mu = s1 * (1.f / 512.f);
;           float var = s2 * (1.f / 512.f) - mu * mu;
;           float rstd = rsqrtf(fmaxf(var, 0.f) + 1e-5f);
; #pragma unroll
;           for (int bj = 0; bj < 2; ++bj)
; #pragma unroll
;             for (int n = 0; n < 2; ++n) {
;               float g = acc[ai][bj][m][n][j];
;               float yn = (bf2f(yv[j][bj][n]) - mu) * rstd * gn[bj][n];
;               Y[(long)(tb + j) * YS + pn * 256 + bj * 128 + wc * 32 + n * 16 + fr] = f2bf(silu_f(g) * yn);
;             }
;         }
	v_lshlrev_b32_e32 v37, 16, v169
	v_sub_f32_e32 v36, v37, v36
	v_mul_f32_e32 v18, v36, v18
	v_mul_f32_e32 v36, 0xbfb8aa3b, v19
	v_exp_f32_e32 v36, v36
	v_mul_f32_e32 v18, v148, v18
	v_add_f32_e32 v36, 1.0, v36
	v_rcp_f32_e32 v36, v36
	s_nop 0
	v_mul_f32_e32 v19, v19, v36
	global_load_dwordx4 v[52:55], v[34:35], off offset:16
	s_nop 0
	global_load_dwordx4 v[34:37], v[34:35], off
	v_mul_f32_e32 v18, v19, v18
	v_cvt_pk_bf16_f32 v50, v18, s0
	s_waitcnt vmcnt(0)
	v_pk_add_f32 v[18:19], v[34:35], v[36:37]
	s_nop 0
	v_pk_add_f32 v[18:19], v[18:19], v[52:53]
	v_mul_f32_e32 v35, 0xbfb8aa3b, v32
	v_pk_add_f32 v[18:19], v[18:19], v[54:55]
	v_exp_f32_e32 v35, v35
	v_pk_mul_f32 v[18:19], v[18:19], s[18:19] op_sel_hi:[1,0]
	v_add_f32_e32 v35, 1.0, v35
	v_fma_f32 v19, -v18, v18, v19
	v_max_f32_e32 v19, 0, v19
	v_add_f32_e32 v19, 0x3727c5ac, v19
	v_cmp_gt_f32_e32 vcc, s25, v19
	v_mul_f32_e32 v34, 0x4b800000, v19
	v_rcp_f32_e32 v35, v35
	v_cndmask_b32_e32 v19, v19, v34, vcc
	v_rsq_f32_e32 v19, v19
	v_mul_f32_e32 v32, v32, v35
	v_mul_f32_e32 v35, 0xbfb8aa3b, v28
	v_mul_f32_e32 v34, 0x45800000, v19
	v_cndmask_b32_e32 v34, v19, v34, vcc
	v_exp_f32_e32 v35, v35
	s_waitcnt vmcnt(0)
	v_lshlrev_b32_e32 v19, 16, v170
	v_sub_f32_e32 v19, v19, v18
	v_mul_f32_e32 v19, v19, v34
	v_mul_f32_e32 v19, v151, v19
	v_mul_f32_e32 v19, v32, v19
	v_add_f32_e32 v35, 1.0, v35
	v_rcp_f32_e32 v35, v35
	v_cvt_pk_bf16_f32 v19, v19, s0
	v_mul_f32_e32 v28, v28, v35
	v_mul_f32_e32 v35, 0xbfb8aa3b, v24
	v_exp_f32_e32 v35, v35
	s_waitcnt vmcnt(0)
	v_lshlrev_b32_e32 v32, 16, v171
	v_sub_f32_e32 v32, v32, v18
	v_mul_f32_e32 v32, v32, v34
	v_mul_f32_e32 v32, v150, v32
	v_mul_f32_e32 v28, v28, v32
	v_add_f32_e32 v35, 1.0, v35
	v_rcp_f32_e32 v35, v35
	v_cvt_pk_bf16_f32 v28, v28, s0
	v_mul_f32_e32 v24, v24, v35
	s_waitcnt vmcnt(0)
	v_lshlrev_b32_e32 v32, 16, v172
	v_sub_f32_e32 v32, v32, v18
	v_mul_f32_e32 v32, v32, v34
	v_mul_f32_e32 v32, v149, v32
	v_mul_f32_e32 v24, v24, v32
	v_cvt_pk_bf16_f32 v24, v24, s0
	s_waitcnt vmcnt(0)
	v_lshlrev_b32_e32 v32, 16, v173
	v_sub_f32_e32 v18, v32, v18
	v_mul_f32_e32 v32, 0xbfb8aa3b, v20
	v_exp_f32_e32 v32, v32
	v_mul_f32_e32 v18, v18, v34
	v_mul_f32_e32 v18, v148, v18
	v_add_f32_e32 v32, 1.0, v32
	v_rcp_f32_e32 v32, v32
	s_nop 0
	v_mul_f32_e32 v20, v20, v32
	v_mul_f32_e32 v18, v20, v18
	global_load_dwordx4 v[34:37], v[38:39], off offset:16
	s_nop 0
	global_load_dwordx4 v[38:41], v[38:39], off
	s_nop 0
	v_cvt_pk_bf16_f32 v18, v18, s0
	global_store_short v[44:45], v0, off
	global_store_short v[44:45], v26, off offset:32
	global_store_short v[44:45], v22, off offset:256
	global_store_short v[44:45], v30, off offset:288
	global_store_short v[46:47], v31, off
	global_store_short v[46:47], v27, off offset:32
	global_store_short v[46:47], v23, off offset:256
	global_store_short v[46:47], v50, off offset:288
	global_store_short v[48:49], v19, off
	global_store_short v[48:49], v28, off offset:32
	global_store_short v[48:49], v24, off offset:256
	global_store_short v[48:49], v18, off offset:288
	v_add_u32_e32 v22, 0xb0, v152
	s_waitcnt vmcnt(0)
	v_pk_add_f32 v[18:19], v[38:39], v[40:41]
	s_nop 0
	v_pk_add_f32 v[18:19], v[18:19], v[34:35]
	s_nop 0
	v_pk_add_f32 v[18:19], v[18:19], v[36:37]
	s_nop 0
	v_pk_mul_f32 v[18:19], v[18:19], s[18:19] op_sel_hi:[1,0]
	s_nop 0
	v_fma_f32 v0, -v18, v18, v19
	v_max_f32_e32 v0, 0, v0
	v_add_f32_e32 v0, 0x3727c5ac, v0
	v_cmp_gt_f32_e32 vcc, s25, v0
	v_mul_f32_e32 v19, 0x4b800000, v0
	s_nop 0
	v_cndmask_b32_e32 v0, v0, v19, vcc
	v_rsq_f32_e32 v0, v0
	s_nop 0
	v_mul_f32_e32 v19, 0x45800000, v0
	v_cndmask_b32_e32 v0, v0, v19, vcc
	s_waitcnt vmcnt(0)
	v_lshlrev_b32_e32 v19, 16, v174
	v_mul_f32_e32 v20, 0xbfb8aa3b, v33
	v_exp_f32_e32 v20, v20
	v_sub_f32_e32 v19, v19, v18
	v_mul_f32_e32 v19, v19, v0
	v_mul_f32_e32 v19, v151, v19
	v_add_f32_e32 v20, 1.0, v20
	v_rcp_f32_e32 v20, v20
	s_nop 0
	v_mul_f32_e32 v20, v33, v20
	v_mul_f32_e32 v19, v20, v19
	v_mul_f32_e32 v20, 0xbfb8aa3b, v29
	v_exp_f32_e32 v20, v20
	v_cvt_pk_bf16_f32 v19, v19, s0
	global_store_short v[42:43], v19, off
	s_waitcnt vmcnt(0)
	v_lshlrev_b32_e32 v19, 16, v175
	v_add_f32_e32 v20, 1.0, v20
	v_rcp_f32_e32 v20, v20
	v_sub_f32_e32 v19, v19, v18
	v_mul_f32_e32 v19, v19, v0
	v_mul_f32_e32 v19, v150, v19
	v_mul_f32_e32 v20, v29, v20
	v_mul_f32_e32 v19, v20, v19
	v_mul_f32_e32 v20, 0xbfb8aa3b, v25
	v_exp_f32_e32 v20, v20
	v_cvt_pk_bf16_f32 v19, v19, s0
	global_store_short v[42:43], v19, off offset:32
	s_waitcnt vmcnt(0)
	v_lshlrev_b32_e32 v19, 16, v176
	v_add_f32_e32 v20, 1.0, v20
	v_rcp_f32_e32 v20, v20
	v_sub_f32_e32 v19, v19, v18
	v_mul_f32_e32 v19, v19, v0
	v_mul_f32_e32 v19, v149, v19
	v_mul_f32_e32 v20, v25, v20
	v_mul_f32_e32 v19, v20, v19
	v_cvt_pk_bf16_f32 v19, v19, s0
	global_store_short v[42:43], v19, off offset:256
	s_waitcnt vmcnt(0)
; __device__ __forceinline__ float bf2f(u16 b) { return __uint_as_float(((unsigned)b) << 16); }
; __device__ __forceinline__ float silu_f(float g) { return g * __builtin_amdgcn_rcpf(1.f + __builtin_amdgcn_exp2f(-g * LOG2E)); }
; template <int EPI>
; __device__ __forceinline__ void epilogue(const Params& p, int pass, int layer, int pm, int pn,
;                                          f32x4 (&acc)[2][2][4][2], const float* xin, float* xout) {
;     ...
;       for (int m = 0; m < 4; ++m) {
;         int tb = t0 + ai * 128 + wr * 64 + m * 16 + fq * 4;
;         asm volatile("" : "+v"(tb));
;         float4 s01[4], s23[4];
;         u16 yv[4][2][2];
; #pragma unroll
;         for (int j = 0; j < 4; ++j) {
;           const float4* sp = (const float4*)(stat + ((long)(tb + j) * 8 + h) * 8);
;           s01[j] = sp[0]; s23[j] = sp[1];
; #pragma unroll
;           for (int bj = 0; bj < 2; ++bj)
; #pragma unroll
;             for (int n = 0; n < 2; ++n)
;               yv[j][bj][n] = Y[(long)(tb + j) * YS + pn * 256 + bj * 128 + wc * 32 + n * 16 + fr];
;         }
; #pragma unroll
;         for (int j = 0; j < 4; ++j) {
;           float s1 = s01[j].x + s01[j].z + s23[j].x + s23[j].z, s2 = s01[j].y + s01[j].w + s23[j].y + s23[j].w;
;           float mu = s1 * (1.f / 512.f);
;           float var = s2 * (1.f / 512.f) - mu * mu;
;           float rstd = rsqrtf(fmaxf(var, 0.f) + 1e-5f);
; #pragma unroll
;           for (int bj = 0; bj < 2; ++bj)
; #pragma unroll
;             for (int n = 0; n < 2; ++n) {
;               float g = acc[ai][bj][m][n][j];
;               float yn = (bf2f(yv[j][bj][n]) - mu) * rstd * gn[bj][n];
;               Y[(long)(tb + j) * YS + pn * 256 + bj * 128 + wc * 32 + n * 16 + fr] = f2bf(silu_f(g) * yn);
;             }
;         }
	v_lshlrev_b32_e32 v19, 16, v177
	v_sub_f32_e32 v18, v19, v18
	v_mul_f32_e32 v0, v18, v0
	v_mul_f32_e32 v18, 0xbfb8aa3b, v21
	v_exp_f32_e32 v18, v18
	v_mul_f32_e32 v0, v148, v0
	v_add_f32_e32 v18, 1.0, v18
	v_rcp_f32_e32 v18, v18
	s_nop 0
	v_mul_f32_e32 v18, v21, v18
	v_mul_f32_e32 v0, v18, v0
	v_cvt_pk_bf16_f32 v0, v0, s0
	global_store_short v[42:43], v0, off offset:288
	s_nop 0
	v_ashrrev_i32_e32 v23, 31, v22
	v_lshlrev_b64 v[18:19], 8, v[22:23]
	v_lshl_add_u64 v[24:25], s[16:17], 0, v[18:19]
	global_load_dwordx4 v[34:37], v[24:25], off offset:16
	global_load_dwordx4 v[38:41], v[24:25], off
	v_mad_i64_i32 v[28:29], s[14:15], v22, s24, v[138:139]
	global_load_ushort v178, v[28:29], off
	global_load_ushort v179, v[28:29], off offset:32
	global_load_ushort v180, v[28:29], off offset:256
	global_load_ushort v181, v[28:29], off offset:288
	v_add_u32_e32 v18, 1, v22
	v_ashrrev_i32_e32 v19, 31, v18
	v_lshlrev_b64 v[20:21], 8, v[18:19]
	v_lshl_add_u64 v[20:21], s[16:17], 0, v[20:21]
	v_mad_i64_i32 v[30:31], s[14:15], v18, s24, v[138:139]
	global_load_ushort v182, v[30:31], off
	global_load_ushort v183, v[30:31], off offset:32
	global_load_ushort v184, v[30:31], off offset:256
	global_load_ushort v185, v[30:31], off offset:288
	v_add_u32_e32 v26, 2, v22
	v_ashrrev_i32_e32 v27, 31, v26
	v_lshlrev_b64 v[18:19], 8, v[26:27]
	v_lshl_add_u64 v[18:19], s[16:17], 0, v[18:19]
	v_mad_i64_i32 v[32:33], s[14:15], v26, s24, v[138:139]
	global_load_ushort v186, v[32:33], off
	global_load_ushort v187, v[32:33], off offset:32
	global_load_ushort v188, v[32:33], off offset:256
	global_load_ushort v189, v[32:33], off offset:288
	v_add_u32_e32 v26, 3, v22
	v_ashrrev_i32_e32 v27, 31, v26
	v_lshlrev_b64 v[22:23], 8, v[26:27]
	v_lshl_add_u64 v[22:23], s[16:17], 0, v[22:23]
	v_mad_i64_i32 v[26:27], s[14:15], v26, s24, v[138:139]
	global_load_ushort v190, v[26:27], off
	global_load_ushort v191, v[26:27], off offset:32
	global_load_ushort v192, v[26:27], off offset:256
	global_load_ushort v193, v[26:27], off offset:288
	s_mov_b32 s14, s6
	s_waitcnt vmcnt(0)
	v_pk_add_f32 v[24:25], v[38:39], v[40:41]
	s_nop 0
	v_pk_add_f32 v[24:25], v[24:25], v[34:35]
	v_mul_f32_e32 v34, 0xbfb8aa3b, v14
	v_pk_add_f32 v[24:25], v[24:25], v[36:37]
	v_exp_f32_e32 v34, v34
	v_pk_mul_f32 v[24:25], v[24:25], s[18:19] op_sel_hi:[1,0]
	v_add_f32_e32 v34, 1.0, v34
	v_fma_f32 v0, -v24, v24, v25
	v_max_f32_e32 v0, 0, v0
	v_add_f32_e32 v0, 0x3727c5ac, v0
	v_cmp_gt_f32_e32 vcc, s25, v0
	v_mul_f32_e32 v25, 0x4b800000, v0
	v_rcp_f32_e32 v34, v34
	v_cndmask_b32_e32 v0, v0, v25, vcc
	v_rsq_f32_e32 v0, v0
	v_mul_f32_e32 v14, v14, v34
	v_mul_f32_e32 v34, 0xbfb8aa3b, v10
	v_mul_f32_e32 v25, 0x45800000, v0
	v_cndmask_b32_e32 v25, v0, v25, vcc
	v_exp_f32_e32 v34, v34
	s_waitcnt vmcnt(0)
	v_lshlrev_b32_e32 v0, 16, v178
	v_sub_f32_e32 v0, v0, v24
	v_mul_f32_e32 v0, v0, v25
	v_mul_f32_e32 v0, v151, v0
	v_mul_f32_e32 v0, v14, v0
	v_add_f32_e32 v34, 1.0, v34
	v_rcp_f32_e32 v34, v34
	v_cvt_pk_bf16_f32 v0, v0, s0
	v_mul_f32_e32 v10, v10, v34
	v_mul_f32_e32 v34, 0xbfb8aa3b, v6
	v_exp_f32_e32 v34, v34
	s_waitcnt vmcnt(0)
	v_lshlrev_b32_e32 v14, 16, v179
	v_sub_f32_e32 v14, v14, v24
	v_mul_f32_e32 v14, v14, v25
	v_mul_f32_e32 v14, v150, v14
	v_mul_f32_e32 v10, v10, v14
	v_add_f32_e32 v34, 1.0, v34
	v_rcp_f32_e32 v34, v34
	v_cvt_pk_bf16_f32 v10, v10, s0
	v_mul_f32_e32 v6, v6, v34
	s_waitcnt vmcnt(0)
	v_lshlrev_b32_e32 v14, 16, v180
	v_sub_f32_e32 v14, v14, v24
	v_mul_f32_e32 v14, v14, v25
	v_mul_f32_e32 v14, v149, v14
	v_mul_f32_e32 v6, v6, v14
	global_load_dwordx4 v[34:37], v[20:21], off offset:16
	global_load_dwordx4 v[38:41], v[20:21], off
	v_cvt_pk_bf16_f32 v6, v6, s0
	s_waitcnt vmcnt(0)
	v_lshlrev_b32_e32 v14, 16, v181
	v_sub_f32_e32 v14, v14, v24
	v_mul_f32_e32 v24, 0xbfb8aa3b, v2
	v_exp_f32_e32 v24, v24
	s_waitcnt vmcnt(0)
	v_pk_add_f32 v[20:21], v[38:39], v[40:41]
	v_mul_f32_e32 v14, v14, v25
	v_pk_add_f32 v[20:21], v[20:21], v[34:35]
	v_add_f32_e32 v24, 1.0, v24
	v_rcp_f32_e32 v24, v24
	v_mul_f32_e32 v14, v148, v14
	v_pk_add_f32 v[20:21], v[20:21], v[36:37]
	v_mul_f32_e32 v2, v2, v24
	v_mul_f32_e32 v2, v2, v14
	v_pk_mul_f32 v[20:21], v[20:21], s[18:19] op_sel_hi:[1,0]
	v_cvt_pk_bf16_f32 v14, v2, s0
	v_fma_f32 v2, -v20, v20, v21
	v_max_f32_e32 v2, 0, v2
	v_add_f32_e32 v2, 0x3727c5ac, v2
	v_cmp_gt_f32_e32 vcc, s25, v2
	v_mul_f32_e32 v21, 0x4b800000, v2
	v_mul_f32_e32 v24, 0xbfb8aa3b, v15
	v_cndmask_b32_e32 v2, v2, v21, vcc
	v_rsq_f32_e32 v2, v2
	v_exp_f32_e32 v24, v24
	v_mul_f32_e32 v21, 0x45800000, v2
	v_cndmask_b32_e32 v2, v2, v21, vcc
	v_add_f32_e32 v24, 1.0, v24
	v_rcp_f32_e32 v24, v24
	s_waitcnt vmcnt(0)
	v_lshlrev_b32_e32 v21, 16, v182
	v_sub_f32_e32 v21, v21, v20
	v_mul_f32_e32 v21, v21, v2
	v_mul_f32_e32 v21, v151, v21
	v_mul_f32_e32 v15, v15, v24
	v_mul_f32_e32 v15, v15, v21
	v_mul_f32_e32 v24, 0xbfb8aa3b, v11
	v_exp_f32_e32 v24, v24
	v_cvt_pk_bf16_f32 v15, v15, s0
	v_add_f32_e32 v24, 1.0, v24
	v_rcp_f32_e32 v24, v24
	s_waitcnt vmcnt(0)
	v_lshlrev_b32_e32 v21, 16, v183
	v_sub_f32_e32 v21, v21, v20
	v_mul_f32_e32 v21, v21, v2
	v_mul_f32_e32 v21, v150, v21
	v_mul_f32_e32 v11, v11, v24
	v_mul_f32_e32 v11, v11, v21
	v_mul_f32_e32 v24, 0xbfb8aa3b, v7
	v_exp_f32_e32 v24, v24
	v_cvt_pk_bf16_f32 v11, v11, s0
	v_add_f32_e32 v24, 1.0, v24
	v_rcp_f32_e32 v24, v24
	s_waitcnt vmcnt(0)
; __device__ __forceinline__ float bf2f(u16 b) { return __uint_as_float(((unsigned)b) << 16); }
; template <int EPI>
; __device__ __forceinline__ void epilogue(const Params& p, int pass, int layer, int pm, int pn,
;                                          f32x4 (&acc)[2][2][4][2], const float* xin, float* xout) {
;     ...
;       for (int m = 0; m < 4; ++m) {
;         int tb = t0 + ai * 128 + wr * 64 + m * 16 + fq * 4;
;         asm volatile("" : "+v"(tb));
;         float4 s01[4], s23[4];
;         u16 yv[4][2][2];
; #pragma unroll
;         for (int j = 0; j < 4; ++j) {
;           const float4* sp = (const float4*)(stat + ((long)(tb + j) * 8 + h) * 8);
;           s01[j] = sp[0]; s23[j] = sp[1];
; #pragma unroll
;           for (int bj = 0; bj < 2; ++bj)
; #pragma unroll
;             for (int n = 0; n < 2; ++n)
;               yv[j][bj][n] = Y[(long)(tb + j) * YS + pn * 256 + bj * 128 + wc * 32 + n * 16 + fr];
;         }
; #pragma unroll
;         for (int j = 0; j < 4; ++j) {
;           float s1 = s01[j].x + s01[j].z + s23[j].x + s23[j].z, s2 = s01[j].y + s01[j].w + s23[j].y + s23[j].w;
;           float mu = s1 * (1.f / 512.f);
;           float var = s2 * (1.f / 512.f) - mu * mu;
;           float rstd = rsqrtf(fmaxf(var, 0.f) + 1e-5f);
; #pragma unroll
;           for (int bj = 0; bj < 2; ++bj)
; #pragma unroll
;             for (int n = 0; n < 2; ++n) {
;               float g = acc[ai][bj][m][n][j];
;               float yn = (bf2f(yv[j][bj][n]) - mu) * rstd * gn[bj][n];
;               Y[(long)(tb + j) * YS + pn * 256 + bj * 128 + wc * 32 + n * 16 + fr] = f2bf(silu_f(g) * yn);
;             }
;         }
;     ...
;   for (int t = blockIdx.x; t < ntiles; t += gridDim.x) {
;     f32x4 acc[2][2][4][2];
; #pragma unroll
;     for (int a = 0; a < 2; ++a)
; #pragma unroll
;       for (int b = 0; b < 2; ++b)
; #pragma unroll
;         for (int c = 0; c < 4; ++c)
; #pragma unroll
;           for (int d = 0; d < 2; ++d) acc[a][b][c][d] = f32x4{0.f, 0.f, 0.f, 0.f};
;     mainloop_8phase(Ap, Bp, K, acc, p.wid, (int)lda);
;     int cpm = pm, cpn = pn, csub = sub;
;     if (t + (int)gridDim.x < ntiles) {
;       tile_ptrs(t + gridDim.x, sub, pm, pn, Ap, Bp);
;       gemm_issue_first(Ap, Bp, K, p.wid, (int)lda);
;     }
;     epilogue<EPI>(p, csub ? pass1 : pass, layer, cpm, cpn, acc, csub ? xin1 : xin, csub ? xout1 : xout);
	v_lshlrev_b32_e32 v21, 16, v184
	v_sub_f32_e32 v21, v21, v20
	v_mul_f32_e32 v21, v21, v2
	v_mul_f32_e32 v21, v149, v21
	v_mul_f32_e32 v7, v7, v24
	v_mul_f32_e32 v7, v7, v21
	v_cvt_pk_bf16_f32 v7, v7, s0
	s_waitcnt vmcnt(0)
	v_lshlrev_b32_e32 v21, 16, v185
	v_sub_f32_e32 v20, v21, v20
	v_mul_f32_e32 v2, v20, v2
	v_mul_f32_e32 v20, 0xbfb8aa3b, v3
	v_exp_f32_e32 v20, v20
	v_mul_f32_e32 v2, v148, v2
	v_add_f32_e32 v20, 1.0, v20
	v_rcp_f32_e32 v20, v20
	s_nop 0
	v_mul_f32_e32 v3, v3, v20
	global_load_dwordx4 v[36:39], v[18:19], off offset:16
	s_nop 0
	global_load_dwordx4 v[18:21], v[18:19], off
	v_mul_f32_e32 v2, v3, v2
	v_cvt_pk_bf16_f32 v34, v2, s0
	s_waitcnt vmcnt(0)
	v_pk_add_f32 v[2:3], v[18:19], v[20:21]
	s_nop 0
	v_pk_add_f32 v[2:3], v[2:3], v[36:37]
	v_mul_f32_e32 v19, 0xbfb8aa3b, v16
	v_pk_add_f32 v[2:3], v[2:3], v[38:39]
	v_exp_f32_e32 v19, v19
	v_pk_mul_f32 v[2:3], v[2:3], s[18:19] op_sel_hi:[1,0]
	v_add_f32_e32 v19, 1.0, v19
	v_fma_f32 v3, -v2, v2, v3
	v_max_f32_e32 v3, 0, v3
	v_add_f32_e32 v3, 0x3727c5ac, v3
	v_cmp_gt_f32_e32 vcc, s25, v3
	v_mul_f32_e32 v18, 0x4b800000, v3
	v_rcp_f32_e32 v19, v19
	v_cndmask_b32_e32 v3, v3, v18, vcc
	v_rsq_f32_e32 v3, v3
	v_mul_f32_e32 v16, v16, v19
	v_mul_f32_e32 v19, 0xbfb8aa3b, v12
	v_mul_f32_e32 v18, 0x45800000, v3
	v_cndmask_b32_e32 v18, v3, v18, vcc
	v_exp_f32_e32 v19, v19
	s_waitcnt vmcnt(0)
	v_lshlrev_b32_e32 v3, 16, v186
	v_sub_f32_e32 v3, v3, v2
	v_mul_f32_e32 v3, v3, v18
	v_mul_f32_e32 v3, v151, v3
	v_mul_f32_e32 v3, v16, v3
	v_add_f32_e32 v19, 1.0, v19
	v_rcp_f32_e32 v19, v19
	v_cvt_pk_bf16_f32 v3, v3, s0
	v_mul_f32_e32 v12, v12, v19
	v_mul_f32_e32 v19, 0xbfb8aa3b, v8
	v_exp_f32_e32 v19, v19
	s_waitcnt vmcnt(0)
	v_lshlrev_b32_e32 v16, 16, v187
	v_sub_f32_e32 v16, v16, v2
	v_mul_f32_e32 v16, v16, v18
	v_mul_f32_e32 v16, v150, v16
	v_mul_f32_e32 v12, v12, v16
	v_add_f32_e32 v19, 1.0, v19
	v_rcp_f32_e32 v19, v19
	v_cvt_pk_bf16_f32 v12, v12, s0
	v_mul_f32_e32 v8, v8, v19
	s_waitcnt vmcnt(0)
	v_lshlrev_b32_e32 v16, 16, v188
	v_sub_f32_e32 v16, v16, v2
	v_mul_f32_e32 v16, v16, v18
	v_mul_f32_e32 v16, v149, v16
	v_mul_f32_e32 v8, v8, v16
	v_cvt_pk_bf16_f32 v8, v8, s0
	s_waitcnt vmcnt(0)
	v_lshlrev_b32_e32 v16, 16, v189
	v_sub_f32_e32 v2, v16, v2
	v_mul_f32_e32 v16, 0xbfb8aa3b, v4
	v_exp_f32_e32 v16, v16
	v_mul_f32_e32 v2, v2, v18
	v_mul_f32_e32 v2, v148, v2
	v_add_f32_e32 v16, 1.0, v16
	v_rcp_f32_e32 v16, v16
	s_nop 0
	v_mul_f32_e32 v4, v4, v16
	v_mul_f32_e32 v2, v4, v2
	global_load_dwordx4 v[18:21], v[22:23], off offset:16
	s_nop 0
	global_load_dwordx4 v[22:25], v[22:23], off
	s_nop 0
	v_cvt_pk_bf16_f32 v2, v2, s0
	global_store_short v[28:29], v0, off
	global_store_short v[28:29], v10, off offset:32
	global_store_short v[28:29], v6, off offset:256
	global_store_short v[28:29], v14, off offset:288
	global_store_short v[30:31], v15, off
	global_store_short v[30:31], v11, off offset:32
	global_store_short v[30:31], v7, off offset:256
	global_store_short v[30:31], v34, off offset:288
	global_store_short v[32:33], v3, off
	global_store_short v[32:33], v12, off offset:32
	global_store_short v[32:33], v8, off offset:256
	global_store_short v[32:33], v2, off offset:288
	s_waitcnt vmcnt(0)
	v_pk_add_f32 v[2:3], v[22:23], v[24:25]
	s_nop 0
	v_pk_add_f32 v[2:3], v[2:3], v[18:19]
	s_nop 0
	v_pk_add_f32 v[2:3], v[2:3], v[20:21]
	s_nop 0
	v_pk_mul_f32 v[2:3], v[2:3], s[18:19] op_sel_hi:[1,0]
	s_nop 0
	v_fma_f32 v0, -v2, v2, v3
	v_max_f32_e32 v0, 0, v0
	v_add_f32_e32 v0, 0x3727c5ac, v0
	v_cmp_gt_f32_e32 vcc, s25, v0
	v_mul_f32_e32 v3, 0x4b800000, v0
	s_nop 0
	v_cndmask_b32_e32 v0, v0, v3, vcc
	v_rsq_f32_e32 v0, v0
	s_nop 0
	v_mul_f32_e32 v3, 0x45800000, v0
	v_cndmask_b32_e32 v0, v0, v3, vcc
	s_waitcnt vmcnt(0)
	v_lshlrev_b32_e32 v3, 16, v190
	v_mul_f32_e32 v4, 0xbfb8aa3b, v17
	v_exp_f32_e32 v4, v4
	v_sub_f32_e32 v3, v3, v2
	v_mul_f32_e32 v3, v3, v0
	v_mul_f32_e32 v3, v151, v3
	v_add_f32_e32 v4, 1.0, v4
	v_rcp_f32_e32 v4, v4
	s_and_b64 vcc, exec, s[4:5]
	v_mul_f32_e32 v4, v17, v4
	v_mul_f32_e32 v3, v4, v3
	v_mul_f32_e32 v4, 0xbfb8aa3b, v13
	v_exp_f32_e32 v4, v4
	v_cvt_pk_bf16_f32 v3, v3, s0
	global_store_short v[26:27], v3, off
	s_waitcnt vmcnt(0)
	v_lshlrev_b32_e32 v3, 16, v191
	v_add_f32_e32 v4, 1.0, v4
	v_rcp_f32_e32 v4, v4
	v_sub_f32_e32 v3, v3, v2
	v_mul_f32_e32 v3, v3, v0
	v_mul_f32_e32 v3, v150, v3
	v_mul_f32_e32 v4, v13, v4
	v_mul_f32_e32 v3, v4, v3
	v_mul_f32_e32 v4, 0xbfb8aa3b, v9
	v_exp_f32_e32 v4, v4
	v_cvt_pk_bf16_f32 v3, v3, s0
	global_store_short v[26:27], v3, off offset:32
	s_waitcnt vmcnt(0)
	v_lshlrev_b32_e32 v3, 16, v192
	v_add_f32_e32 v4, 1.0, v4
	v_rcp_f32_e32 v4, v4
	v_sub_f32_e32 v3, v3, v2
	v_mul_f32_e32 v3, v3, v0
	v_mul_f32_e32 v3, v149, v3
	v_mul_f32_e32 v4, v9, v4
	v_mul_f32_e32 v3, v4, v3
	v_cvt_pk_bf16_f32 v3, v3, s0
	global_store_short v[26:27], v3, off offset:256
	s_waitcnt vmcnt(0)
	v_lshlrev_b32_e32 v3, 16, v193
	v_sub_f32_e32 v2, v3, v2
	v_mul_f32_e32 v0, v2, v0
	v_mul_f32_e32 v2, 0xbfb8aa3b, v5
	v_exp_f32_e32 v2, v2
	v_mul_f32_e32 v0, v148, v0
	v_add_f32_e32 v2, 1.0, v2
	v_rcp_f32_e32 v2, v2
	s_nop 0
	v_mul_f32_e32 v2, v5, v2
	v_mul_f32_e32 v0, v2, v0
	v_cvt_pk_bf16_f32 v0, v0, s0
	global_store_short v[26:27], v0, off offset:288
	s_cbranch_vccnz .LBB0_66
